# mout epilogues: second-half gate loads (ov/zv, ai=1) issued with the first half's into spare VGPRs; store-drain waits dropped
# baseline (speedup 1.0000x reference)
.LBB0_614:
	s_or_b64 exec, exec, s[20:21]
	s_add_u32 s3, s24, s19
	s_addc_u32 s21, s25, 0
	v_mov_b32_e32 v32, v182
	s_add_u32 s20, s3, 0x8801000
	s_waitcnt lgkmcnt(0)
	s_barrier
	s_mov_b64 s[98:99], 0xc0000
	s_addc_u32 s21, s21, 0
	v_and_b32_e32 v34, 63, v32
	s_lshl_b64 s[0:1], s[0:1], 1
	s_add_u32 s0, s63, s0
	v_ashrrev_i32_e32 v32, 1, v34
	s_addc_u32 s1, s64, s1
	v_and_b32_e32 v32, -8, v32
	s_add_u32 s0, s0, s19
	v_add_u32_e32 v32, s80, v32
	s_addc_u32 s1, s1, 0
	s_lshl_b32 s2, s2, 2
	v_ashrrev_i32_e32 v33, 31, v32
	v_and_or_b32 v174, v34, 15, s79
	v_mov_b64_e32 v[172:173], s[20:21]
	s_add_u32 s2, s46, s2
	v_mad_i64_i32 v[34:35], s[20:21], v174, s77, v[172:173]
	v_lshlrev_b64 v[86:87], 1, v[32:33]
	s_addc_u32 s3, s47, 0
	v_lshl_add_u64 v[34:35], v[34:35], 0, v[86:87]
	v_lshl_add_u64 v[236:237], v[34:35], 0, s[98:99]
	global_load_dwordx4 v[186:189], v[34:35], off nt
	v_lshl_add_u64 v[32:33], v[32:33], 2, s[2:3]
	global_load_dwordx4 v[44:47], v[32:33], off
	global_load_dwordx4 v[36:39], v[32:33], off offset:16
	v_or_b32_e32 v180, 16, v174
	v_or_b32_e32 v178, 32, v174
	v_mad_i64_i32 v[40:41], s[2:3], v180, s77, v[172:173]
	v_mad_i64_i32 v[42:43], s[2:3], v178, s77, v[172:173]
	v_lshl_add_u32 v152, v174, 2, 0
	v_lshl_add_u64 v[40:41], v[40:41], 0, v[86:87]
	v_lshl_add_u64 v[42:43], v[42:43], 0, v[86:87]
	global_load_dwordx4 v[190:193], v[34:35], off offset:256 nt
	v_lshl_add_u64 v[238:239], v[40:41], 0, s[98:99]
	global_load_dwordx4 v[68:71], v[40:41], off nt
	global_load_dwordx4 v[64:67], v[40:41], off offset:256 nt
	v_lshl_add_u64 v[240:241], v[42:43], 0, s[98:99]
	global_load_dwordx4 v[60:63], v[42:43], off nt
	global_load_dwordx4 v[56:59], v[42:43], off offset:256 nt
	ds_read_b32 v35, v152
	ds_read_b32 v41, v152 offset:1024
	ds_read_b32 v43, v152 offset:2048
	ds_read_b32 v197, v152 offset:3072
	ds_read_b32 v34, v152 offset:4096
	ds_read_b32 v40, v152 offset:5120
	ds_read_b32 v42, v152 offset:6144
	ds_read_b32 v196, v152 offset:7168
	v_or_b32_e32 v176, 48, v174
	v_ashrrev_i32_e32 v175, 31, v174
	s_waitcnt lgkmcnt(0)
	v_pk_add_f32 v[34:35], v[34:35], v[40:41]
	v_mad_i64_i32 v[48:49], s[2:3], v176, s77, v[172:173]
	v_pk_add_f32 v[34:35], v[34:35], v[42:43]
	v_lshlrev_b64 v[50:51], 11, v[174:175]
	v_pk_add_f32 v[34:35], v[34:35], v[196:197]
	v_lshl_add_u64 v[48:49], v[48:49], 0, v[86:87]
	v_pk_mul_f32 v[196:197], v[34:35], s[16:17] op_sel_hi:[1,0]
	v_lshl_add_u64 v[194:195], s[0:1], 0, v[50:51]
	v_fma_f32 v34, -v197, v197, v196
	v_max_f32_e32 v34, 0, v34
	v_add_f32_e32 v34, 0x358637bd, v34
	v_mul_f32_e32 v35, 0x4b800000, v34
	v_cmp_gt_f32_e32 vcc, s78, v34
	v_lshl_add_u64 v[242:243], v[48:49], 0, s[98:99]
	global_load_dwordx4 v[52:55], v[48:49], off nt
	s_nop 0
	global_load_dwordx4 v[48:51], v[48:49], off offset:256 nt
	v_cndmask_b32_e32 v34, v34, v35, vcc
	v_rsq_f32_e32 v175, v34
	global_load_dwordx4 v[40:43], v[32:33], off offset:512
	s_nop 0
	global_load_dwordx4 v[32:35], v[32:33], off offset:528
	global_load_dwordx4 v[204:207], v[236:237], off nt
	global_load_dwordx4 v[208:211], v[236:237], off offset:256 nt
	global_load_dwordx4 v[212:215], v[238:239], off nt
	global_load_dwordx4 v[216:219], v[238:239], off offset:256 nt
	global_load_dwordx4 v[220:223], v[240:241], off nt
	global_load_dwordx4 v[224:227], v[240:241], off offset:256 nt
	global_load_dwordx4 v[228:231], v[242:243], off nt
	global_load_dwordx4 v[232:235], v[242:243], off offset:256 nt
	v_pk_add_f32 v[28:29], v[28:29], v[196:197] op_sel:[0,1] neg_lo:[0,1] neg_hi:[0,1]
	v_pk_add_f32 v[30:31], v[30:31], v[196:197] op_sel:[0,1] neg_lo:[0,1] neg_hi:[0,1]
	v_mul_f32_e32 v177, 0x45800000, v175
	v_cndmask_b32_e32 v198, v175, v177, vcc
	v_pk_mul_f32 v[28:29], v[28:29], v[198:199] op_sel_hi:[1,0]
	v_pk_mul_f32 v[30:31], v[30:31], v[198:199] op_sel_hi:[1,0]
	v_pk_add_f32 v[166:167], v[166:167], v[196:197] op_sel:[0,1] neg_lo:[0,1] neg_hi:[0,1]
	v_pk_add_f32 v[150:151], v[150:151], v[196:197] op_sel:[0,1] neg_lo:[0,1] neg_hi:[0,1]
	v_pk_mul_f32 v[166:167], v[166:167], v[198:199] op_sel_hi:[1,0]
	v_pk_mul_f32 v[150:151], v[150:151], v[198:199] op_sel_hi:[1,0]
	v_pk_add_f32 v[164:165], v[164:165], v[196:197] op_sel:[0,1] neg_lo:[0,1] neg_hi:[0,1]
	v_pk_add_f32 v[148:149], v[148:149], v[196:197] op_sel:[0,1] neg_lo:[0,1] neg_hi:[0,1]
	v_pk_mul_f32 v[164:165], v[164:165], v[198:199] op_sel_hi:[1,0]
	v_pk_mul_f32 v[148:149], v[148:149], v[198:199] op_sel_hi:[1,0]
	v_pk_add_f32 v[140:141], v[140:141], v[196:197] op_sel:[0,1] neg_lo:[0,1] neg_hi:[0,1]
	v_ashrrev_i32_e32 v181, 31, v180
	v_pk_mul_f32 v[140:141], v[140:141], v[198:199] op_sel_hi:[1,0]
	s_add_i32 s18, s18, s96
	s_add_i32 s69, s69, s70
	s_add_i32 s71, s71, s72
	s_cmpk_gt_i32 s18, 0xff
	s_waitcnt vmcnt(8)
	v_lshlrev_b32_e32 v200, 16, v186
	v_and_b32_e32 v201, 0xffff0000, v186
	v_mul_f32_e32 v175, 0xbfb8aa3b, v200
	v_mul_f32_e32 v177, 0xbfb8aa3b, v201
	v_exp_f32_e32 v175, v175
	v_exp_f32_e32 v177, v177
	v_lshlrev_b32_e32 v186, 16, v187
	v_and_b32_e32 v187, 0xffff0000, v187
	v_add_f32_e32 v175, 1.0, v175
	v_mul_f32_e32 v179, 0xbfb8aa3b, v186
	v_add_f32_e32 v177, 1.0, v177
	v_rcp_f32_e32 v202, v175
	v_mul_f32_e32 v175, 0xbfb8aa3b, v187
	v_rcp_f32_e32 v203, v177
	v_exp_f32_e32 v177, v179
	v_exp_f32_e32 v175, v175
	v_pk_mul_f32 v[28:29], v[44:45], v[28:29]
	v_pk_mul_f32 v[200:201], v[202:203], v[200:201]
	v_add_f32_e32 v177, 1.0, v177
	v_add_f32_e32 v175, 1.0, v175
	v_pk_mul_f32 v[28:29], v[200:201], v[28:29]
	v_rcp_f32_e32 v200, v177
	v_rcp_f32_e32 v201, v175
	v_pk_mul_f32 v[30:31], v[46:47], v[30:31]
	v_pk_mul_f32 v[166:167], v[36:37], v[166:167]
	v_cvt_pk_bf16_f32 v28, v28, v29
	v_pk_mul_f32 v[186:187], v[200:201], v[186:187]
	v_lshlrev_b32_e32 v200, 16, v188
	v_and_b32_e32 v201, 0xffff0000, v188
	v_mul_f32_e32 v175, 0xbfb8aa3b, v200
	v_exp_f32_e32 v175, v175
	v_mul_f32_e32 v177, 0xbfb8aa3b, v201
	v_exp_f32_e32 v177, v177
	v_pk_mul_f32 v[30:31], v[186:187], v[30:31]
	v_add_f32_e32 v175, 1.0, v175
	v_rcp_f32_e32 v186, v175
	v_add_f32_e32 v175, 1.0, v177
	v_lshlrev_b32_e32 v188, 16, v189
	v_rcp_f32_e32 v187, v175
	v_and_b32_e32 v189, 0xffff0000, v189
	v_mul_f32_e32 v175, 0xbfb8aa3b, v188
	v_exp_f32_e32 v175, v175
	v_mul_f32_e32 v177, 0xbfb8aa3b, v189
	v_exp_f32_e32 v177, v177
	v_pk_mul_f32 v[186:187], v[186:187], v[200:201]
	v_add_f32_e32 v175, 1.0, v175
	v_pk_mul_f32 v[166:167], v[186:187], v[166:167]
	v_rcp_f32_e32 v186, v175
	v_add_f32_e32 v175, 1.0, v177
	v_rcp_f32_e32 v187, v175
	v_cvt_pk_bf16_f32 v29, v30, v31
	v_cvt_pk_bf16_f32 v30, v166, v167
	v_lshlrev_b32_e32 v166, 16, v190
	v_and_b32_e32 v167, 0xffff0000, v190
	v_mul_f32_e32 v175, 0xbfb8aa3b, v166
	v_mul_f32_e32 v177, 0xbfb8aa3b, v167
	v_exp_f32_e32 v175, v175
	v_exp_f32_e32 v177, v177
	v_pk_mul_f32 v[150:151], v[38:39], v[150:151]
	v_pk_mul_f32 v[186:187], v[186:187], v[188:189]
	s_waitcnt lgkmcnt(0)
	v_pk_mul_f32 v[164:165], v[42:43], v[164:165]
	v_pk_mul_f32 v[150:151], v[186:187], v[150:151]
	v_pk_mul_f32 v[148:149], v[32:33], v[148:149]
	v_cvt_pk_bf16_f32 v31, v150, v151
	v_lshl_add_u64 v[150:151], v[194:195], 0, v[86:87]
	global_store_dwordx4 v[150:151], v[28:31], off
	v_pk_mul_f32 v[140:141], v[34:35], v[140:141]
	v_ashrrev_i32_e32 v179, 31, v178
	v_add_f32_e32 v28, 1.0, v175
	v_add_f32_e32 v29, 1.0, v177
	v_rcp_f32_e32 v28, v28
	v_rcp_f32_e32 v29, v29
	v_pk_add_f32 v[30:31], v[170:171], v[196:197] op_sel:[0,1] neg_lo:[0,1] neg_hi:[0,1]
	v_ashrrev_i32_e32 v177, 31, v176
	v_pk_mul_f32 v[30:31], v[30:31], v[198:199] op_sel_hi:[1,0]
	v_pk_mul_f32 v[28:29], v[28:29], v[166:167]
	v_lshlrev_b32_e32 v166, 16, v191
	v_and_b32_e32 v167, 0xffff0000, v191
	v_mul_f32_e32 v170, 0xbfb8aa3b, v166
	v_mul_f32_e32 v171, 0xbfb8aa3b, v167
	v_exp_f32_e32 v170, v170
	v_exp_f32_e32 v171, v171
	v_pk_mul_f32 v[30:31], v[40:41], v[30:31]
	s_nop 0
	v_pk_mul_f32 v[28:29], v[28:29], v[30:31]
	v_add_f32_e32 v30, 1.0, v170
	v_add_f32_e32 v31, 1.0, v171
	v_rcp_f32_e32 v30, v30
	v_rcp_f32_e32 v31, v31
	v_cvt_pk_bf16_f32 v28, v28, v29
	v_pk_mul_f32 v[30:31], v[30:31], v[166:167]
	v_lshlrev_b32_e32 v166, 16, v192
	v_and_b32_e32 v167, 0xffff0000, v192
	v_mul_f32_e32 v170, 0xbfb8aa3b, v166
	v_mul_f32_e32 v171, 0xbfb8aa3b, v167
	v_exp_f32_e32 v170, v170
	v_exp_f32_e32 v171, v171
	v_pk_mul_f32 v[30:31], v[30:31], v[164:165]
	v_add_f32_e32 v164, 1.0, v170
	v_add_f32_e32 v165, 1.0, v171
	v_rcp_f32_e32 v164, v164
	v_rcp_f32_e32 v165, v165
	v_cvt_pk_bf16_f32 v29, v30, v31
	v_pk_mul_f32 v[164:165], v[164:165], v[166:167]
	v_lshlrev_b32_e32 v166, 16, v193
	v_and_b32_e32 v167, 0xffff0000, v193
	v_mul_f32_e32 v170, 0xbfb8aa3b, v166
	v_mul_f32_e32 v171, 0xbfb8aa3b, v167
	v_exp_f32_e32 v170, v170
	v_exp_f32_e32 v171, v171
	v_pk_mul_f32 v[148:149], v[164:165], v[148:149]
	v_add_f32_e32 v164, 1.0, v170
	v_add_f32_e32 v165, 1.0, v171
	v_rcp_f32_e32 v164, v164
	v_rcp_f32_e32 v165, v165
	v_cvt_pk_bf16_f32 v30, v148, v149
	v_pk_mul_f32 v[164:165], v[164:165], v[166:167]
	s_nop 0
	v_pk_mul_f32 v[140:141], v[164:165], v[140:141]
	s_nop 0
	v_cvt_pk_bf16_f32 v31, v140, v141
	global_store_dwordx4 v[150:151], v[28:31], off offset:256
	ds_read_b32 v29, v152 offset:64
	ds_read_b32 v31, v152 offset:1088
	ds_read_b32 v141, v152 offset:2112
	ds_read_b32 v149, v152 offset:3136
	ds_read_b32 v28, v152 offset:4160
	ds_read_b32 v30, v152 offset:5184
	ds_read_b32 v140, v152 offset:6208
	ds_read_b32 v148, v152 offset:7232
	s_waitcnt lgkmcnt(0)
	v_pk_add_f32 v[28:29], v[28:29], v[30:31]
	s_nop 0
	v_pk_add_f32 v[28:29], v[28:29], v[140:141]
	v_lshlrev_b64 v[140:141], 11, v[180:181]
	v_pk_add_f32 v[28:29], v[28:29], v[148:149]
	v_lshlrev_b32_e32 v148, 16, v68
	v_pk_mul_f32 v[28:29], v[28:29], s[16:17] op_sel_hi:[1,0]
	v_and_b32_e32 v149, 0xffff0000, v68
	v_fma_f32 v30, -v29, v29, v28
	v_max_f32_e32 v30, 0, v30
	v_add_f32_e32 v30, 0x358637bd, v30
	v_mul_f32_e32 v31, 0x4b800000, v30
	v_cmp_gt_f32_e32 vcc, s78, v30
	v_mul_f32_e32 v68, 0xbfb8aa3b, v149
	v_exp_f32_e32 v68, v68
	v_cndmask_b32_e32 v30, v30, v31, vcc
	v_rsq_f32_e32 v30, v30
	v_pk_add_f32 v[20:21], v[20:21], v[28:29] op_sel:[0,1] neg_lo:[0,1] neg_hi:[0,1]
	v_pk_add_f32 v[22:23], v[22:23], v[28:29] op_sel:[0,1] neg_lo:[0,1] neg_hi:[0,1]
	v_pk_add_f32 v[136:137], v[136:137], v[28:29] op_sel:[0,1] neg_lo:[0,1] neg_hi:[0,1]
	v_mul_f32_e32 v31, 0x45800000, v30
	v_cndmask_b32_e32 v30, v30, v31, vcc
	v_mul_f32_e32 v31, 0xbfb8aa3b, v148
	v_exp_f32_e32 v31, v31
	v_lshl_add_u64 v[140:141], s[0:1], 0, v[140:141]
	v_pk_add_f32 v[130:131], v[130:131], v[28:29] op_sel:[0,1] neg_lo:[0,1] neg_hi:[0,1]
	v_add_f32_e32 v31, 1.0, v31
	v_rcp_f32_e32 v150, v31
	v_add_f32_e32 v31, 1.0, v68
	v_rcp_f32_e32 v151, v31
	v_lshlrev_b32_e32 v68, 16, v69
	v_pk_mul_f32 v[20:21], v[20:21], v[30:31] op_sel_hi:[1,0]
	v_and_b32_e32 v69, 0xffff0000, v69
	v_mul_f32_e32 v31, 0xbfb8aa3b, v68
	v_pk_mul_f32 v[148:149], v[150:151], v[148:149]
	v_exp_f32_e32 v31, v31
	v_mul_f32_e32 v150, 0xbfb8aa3b, v69
	v_exp_f32_e32 v150, v150
	v_pk_mul_f32 v[20:21], v[44:45], v[20:21]
	v_add_f32_e32 v31, 1.0, v31
	v_pk_mul_f32 v[20:21], v[148:149], v[20:21]
	v_rcp_f32_e32 v148, v31
	v_add_f32_e32 v31, 1.0, v150
	v_rcp_f32_e32 v149, v31
	v_pk_mul_f32 v[22:23], v[22:23], v[30:31] op_sel_hi:[1,0]
	v_pk_add_f32 v[150:151], v[154:155], v[28:29] op_sel:[0,1] neg_lo:[0,1] neg_hi:[0,1]
	v_pk_mul_f32 v[22:23], v[46:47], v[22:23]
	v_pk_mul_f32 v[68:69], v[148:149], v[68:69]
	v_lshlrev_b32_e32 v148, 16, v70
	v_and_b32_e32 v149, 0xffff0000, v70
	v_mul_f32_e32 v31, 0xbfb8aa3b, v148
	v_exp_f32_e32 v31, v31
	v_mul_f32_e32 v70, 0xbfb8aa3b, v149
	v_exp_f32_e32 v70, v70
	v_pk_mul_f32 v[22:23], v[68:69], v[22:23]
	v_add_f32_e32 v31, 1.0, v31
	v_rcp_f32_e32 v68, v31
	v_add_f32_e32 v31, 1.0, v70
	v_rcp_f32_e32 v69, v31
	v_lshlrev_b32_e32 v70, 16, v71
	v_pk_mul_f32 v[150:151], v[150:151], v[30:31] op_sel_hi:[1,0]
	v_and_b32_e32 v71, 0xffff0000, v71
	v_mul_f32_e32 v31, 0xbfb8aa3b, v70
	v_pk_mul_f32 v[68:69], v[68:69], v[148:149]
	v_exp_f32_e32 v31, v31
	v_mul_f32_e32 v148, 0xbfb8aa3b, v71
	v_exp_f32_e32 v149, v148
	v_cvt_pk_bf16_f32 v20, v20, v21
	v_add_f32_e32 v31, 1.0, v31
	v_rcp_f32_e32 v148, v31
	v_add_f32_e32 v31, 1.0, v149
	v_rcp_f32_e32 v149, v31
	v_pk_mul_f32 v[136:137], v[136:137], v[30:31] op_sel_hi:[1,0]
	v_cvt_pk_bf16_f32 v21, v22, v23
	v_pk_mul_f32 v[136:137], v[38:39], v[136:137]
	v_pk_mul_f32 v[70:71], v[148:149], v[70:71]
	v_pk_mul_f32 v[150:151], v[36:37], v[150:151]
	v_pk_mul_f32 v[70:71], v[70:71], v[136:137]
	v_pk_mul_f32 v[68:69], v[68:69], v[150:151]
	v_cvt_pk_bf16_f32 v23, v70, v71
	v_lshlrev_b32_e32 v70, 16, v64
	v_and_b32_e32 v71, 0xffff0000, v64
	v_mul_f32_e32 v31, 0xbfb8aa3b, v70
	v_mul_f32_e32 v64, 0xbfb8aa3b, v71
	v_exp_f32_e32 v31, v31
	v_exp_f32_e32 v64, v64
	v_cvt_pk_bf16_f32 v22, v68, v69
	v_lshl_add_u64 v[68:69], v[140:141], 0, v[86:87]
	global_store_dwordx4 v[68:69], v[20:23], off
	s_nop 1
	v_add_f32_e32 v20, 1.0, v31
	v_add_f32_e32 v21, 1.0, v64
	v_rcp_f32_e32 v20, v20
	v_rcp_f32_e32 v21, v21
	v_pk_add_f32 v[22:23], v[168:169], v[28:29] op_sel:[0,1] neg_lo:[0,1] neg_hi:[0,1]
	v_lshlrev_b32_e32 v64, 16, v65
	v_and_b32_e32 v65, 0xffff0000, v65
	v_pk_mul_f32 v[22:23], v[22:23], v[30:31] op_sel_hi:[1,0]
	v_pk_mul_f32 v[20:21], v[20:21], v[70:71]
	v_mul_f32_e32 v31, 0xbfb8aa3b, v64
	v_mul_f32_e32 v70, 0xbfb8aa3b, v65
	v_exp_f32_e32 v31, v31
	v_exp_f32_e32 v70, v70
	v_pk_mul_f32 v[22:23], v[40:41], v[22:23]
	s_nop 0
	v_pk_mul_f32 v[20:21], v[20:21], v[22:23]
	v_add_f32_e32 v22, 1.0, v31
	v_add_f32_e32 v23, 1.0, v70
	v_rcp_f32_e32 v22, v22
	v_rcp_f32_e32 v23, v23
	v_pk_add_f32 v[70:71], v[156:157], v[28:29] op_sel:[0,1] neg_lo:[0,1] neg_hi:[0,1]
	v_pk_add_f32 v[28:29], v[120:121], v[28:29] op_sel:[0,1] neg_lo:[0,1] neg_hi:[0,1]
	v_pk_mul_f32 v[70:71], v[70:71], v[30:31] op_sel_hi:[1,0]
	v_pk_mul_f32 v[22:23], v[22:23], v[64:65]
	v_lshlrev_b32_e32 v64, 16, v66
	v_and_b32_e32 v65, 0xffff0000, v66
	v_mul_f32_e32 v31, 0xbfb8aa3b, v64
	v_exp_f32_e32 v31, v31
	v_mul_f32_e32 v66, 0xbfb8aa3b, v65
	v_exp_f32_e32 v66, v66
	v_pk_mul_f32 v[70:71], v[42:43], v[70:71]
	v_add_f32_e32 v31, 1.0, v31
	v_pk_mul_f32 v[22:23], v[22:23], v[70:71]
	v_rcp_f32_e32 v70, v31
	v_add_f32_e32 v31, 1.0, v66
	v_rcp_f32_e32 v71, v31
	v_lshlrev_b32_e32 v66, 16, v67
	v_pk_mul_f32 v[130:131], v[130:131], v[30:31] op_sel_hi:[1,0]
	v_and_b32_e32 v67, 0xffff0000, v67
	v_mul_f32_e32 v31, 0xbfb8aa3b, v66
	v_pk_mul_f32 v[64:65], v[70:71], v[64:65]
	v_exp_f32_e32 v31, v31
	v_mul_f32_e32 v70, 0xbfb8aa3b, v67
	v_exp_f32_e32 v71, v70
	v_pk_mul_f32 v[130:131], v[32:33], v[130:131]
	v_add_f32_e32 v31, 1.0, v31
	v_rcp_f32_e32 v70, v31
	v_add_f32_e32 v31, 1.0, v71
	v_rcp_f32_e32 v71, v31
	v_pk_mul_f32 v[28:29], v[28:29], v[30:31] op_sel_hi:[1,0]
	v_pk_mul_f32 v[64:65], v[64:65], v[130:131]
	v_pk_mul_f32 v[28:29], v[34:35], v[28:29]
	v_pk_mul_f32 v[30:31], v[70:71], v[66:67]
	v_cvt_pk_bf16_f32 v20, v20, v21
	v_pk_mul_f32 v[28:29], v[30:31], v[28:29]
	v_cvt_pk_bf16_f32 v21, v22, v23
	v_cvt_pk_bf16_f32 v22, v64, v65
	v_cvt_pk_bf16_f32 v23, v28, v29
	global_store_dwordx4 v[68:69], v[20:23], off offset:256
	ds_read_b32 v21, v152 offset:128
	ds_read_b32 v23, v152 offset:1152
	ds_read_b32 v29, v152 offset:2176
	ds_read_b32 v31, v152 offset:3200
	ds_read_b32 v20, v152 offset:4224
	ds_read_b32 v22, v152 offset:5248
	ds_read_b32 v28, v152 offset:6272
	ds_read_b32 v30, v152 offset:7296
	v_add_u32_e32 v70, 0x80, v174
	v_ashrrev_i32_e32 v71, 31, v70
	s_waitcnt lgkmcnt(0)
	v_pk_add_f32 v[20:21], v[20:21], v[22:23]
	s_nop 0
	v_pk_add_f32 v[20:21], v[20:21], v[28:29]
	v_lshlrev_b64 v[28:29], 11, v[178:179]
	v_pk_add_f32 v[20:21], v[20:21], v[30:31]
	v_lshlrev_b32_e32 v30, 16, v60
	v_pk_mul_f32 v[20:21], v[20:21], s[16:17] op_sel_hi:[1,0]
	v_and_b32_e32 v31, 0xffff0000, v60
	v_fma_f32 v22, -v21, v21, v20
	v_max_f32_e32 v22, 0, v22
	v_add_f32_e32 v22, 0x358637bd, v22
	v_mul_f32_e32 v23, 0x4b800000, v22
	v_cmp_gt_f32_e32 vcc, s78, v22
	v_mul_f32_e32 v60, 0xbfb8aa3b, v31
	v_exp_f32_e32 v60, v60
	v_cndmask_b32_e32 v22, v22, v23, vcc
	v_rsq_f32_e32 v22, v22
	v_pk_add_f32 v[16:17], v[16:17], v[20:21] op_sel:[0,1] neg_lo:[0,1] neg_hi:[0,1]
	v_pk_add_f32 v[18:19], v[18:19], v[20:21] op_sel:[0,1] neg_lo:[0,1] neg_hi:[0,1]
	v_lshl_add_u64 v[28:29], s[0:1], 0, v[28:29]
	v_mul_f32_e32 v23, 0x45800000, v22
	v_cndmask_b32_e32 v22, v22, v23, vcc
	v_mul_f32_e32 v23, 0xbfb8aa3b, v30
	v_exp_f32_e32 v23, v23
	v_lshl_add_u64 v[28:29], v[28:29], 0, v[86:87]
	v_add_f32_e32 v23, 1.0, v23
	v_rcp_f32_e32 v64, v23
	v_add_f32_e32 v23, 1.0, v60
	v_rcp_f32_e32 v65, v23
	v_lshlrev_b32_e32 v60, 16, v61
	v_pk_mul_f32 v[16:17], v[16:17], v[22:23] op_sel_hi:[1,0]
	v_and_b32_e32 v61, 0xffff0000, v61
	v_mul_f32_e32 v23, 0xbfb8aa3b, v60
	v_pk_mul_f32 v[30:31], v[64:65], v[30:31]
	v_exp_f32_e32 v23, v23
	v_mul_f32_e32 v64, 0xbfb8aa3b, v61
	v_exp_f32_e32 v64, v64
	v_pk_mul_f32 v[16:17], v[44:45], v[16:17]
	v_add_f32_e32 v23, 1.0, v23
	v_pk_mul_f32 v[16:17], v[30:31], v[16:17]
	v_rcp_f32_e32 v30, v23
	v_add_f32_e32 v23, 1.0, v64
	v_rcp_f32_e32 v31, v23
	v_pk_mul_f32 v[18:19], v[18:19], v[22:23] op_sel_hi:[1,0]
	v_pk_add_f32 v[64:65], v[134:135], v[20:21] op_sel:[0,1] neg_lo:[0,1] neg_hi:[0,1]
	v_pk_mul_f32 v[18:19], v[46:47], v[18:19]
	v_pk_mul_f32 v[30:31], v[30:31], v[60:61]
	v_lshlrev_b32_e32 v60, 16, v62
	v_and_b32_e32 v61, 0xffff0000, v62
	v_mul_f32_e32 v23, 0xbfb8aa3b, v60
	v_exp_f32_e32 v23, v23
	v_mul_f32_e32 v62, 0xbfb8aa3b, v61
	v_exp_f32_e32 v62, v62
	v_pk_mul_f32 v[18:19], v[30:31], v[18:19]
	v_add_f32_e32 v23, 1.0, v23
	v_rcp_f32_e32 v30, v23
	v_add_f32_e32 v23, 1.0, v62
	v_rcp_f32_e32 v31, v23
	v_pk_mul_f32 v[64:65], v[64:65], v[22:23] op_sel_hi:[1,0]
	v_cvt_pk_bf16_f32 v16, v16, v17
	v_pk_mul_f32 v[64:65], v[36:37], v[64:65]
	v_pk_mul_f32 v[30:31], v[30:31], v[60:61]
	v_lshlrev_b32_e32 v60, 16, v63
	v_and_b32_e32 v61, 0xffff0000, v63
	v_mul_f32_e32 v23, 0xbfb8aa3b, v60
	v_exp_f32_e32 v23, v23
	v_mul_f32_e32 v62, 0xbfb8aa3b, v61
	v_exp_f32_e32 v63, v62
	v_pk_mul_f32 v[30:31], v[30:31], v[64:65]
	v_add_f32_e32 v23, 1.0, v23
	v_rcp_f32_e32 v62, v23
	v_add_f32_e32 v23, 1.0, v63
	v_rcp_f32_e32 v63, v23
	v_pk_add_f32 v[64:65], v[116:117], v[20:21] op_sel:[0,1] neg_lo:[0,1] neg_hi:[0,1]
	v_cvt_pk_bf16_f32 v17, v18, v19
	v_cvt_pk_bf16_f32 v18, v30, v31
	v_lshlrev_b32_e32 v30, 16, v56
	v_and_b32_e32 v31, 0xffff0000, v56
	v_pk_mul_f32 v[64:65], v[64:65], v[22:23] op_sel_hi:[1,0]
	v_mul_f32_e32 v23, 0xbfb8aa3b, v30
	v_mul_f32_e32 v56, 0xbfb8aa3b, v31
	v_exp_f32_e32 v23, v23
	v_exp_f32_e32 v56, v56
	v_pk_mul_f32 v[64:65], v[38:39], v[64:65]
	v_pk_mul_f32 v[60:61], v[62:63], v[60:61]
	s_nop 0
	v_pk_mul_f32 v[60:61], v[60:61], v[64:65]
	s_nop 0
	v_cvt_pk_bf16_f32 v19, v60, v61
	global_store_dwordx4 v[28:29], v[16:19], off
	v_pk_add_f32 v[60:61], v[114:115], v[20:21] op_sel:[0,1] neg_lo:[0,1] neg_hi:[0,1]
	s_nop 0
	v_add_f32_e32 v16, 1.0, v23
	v_add_f32_e32 v17, 1.0, v56
	v_rcp_f32_e32 v16, v16
	v_rcp_f32_e32 v17, v17
	v_pk_add_f32 v[18:19], v[160:161], v[20:21] op_sel:[0,1] neg_lo:[0,1] neg_hi:[0,1]
	v_pk_mul_f32 v[16:17], v[16:17], v[30:31]
	v_lshlrev_b32_e32 v30, 16, v57
	v_and_b32_e32 v31, 0xffff0000, v57
	v_pk_mul_f32 v[18:19], v[18:19], v[22:23] op_sel_hi:[1,0]
	v_mul_f32_e32 v23, 0xbfb8aa3b, v30
	v_mul_f32_e32 v56, 0xbfb8aa3b, v31
	v_exp_f32_e32 v23, v23
	v_exp_f32_e32 v56, v56
	v_pk_mul_f32 v[18:19], v[40:41], v[18:19]
	s_nop 0
	v_pk_mul_f32 v[16:17], v[16:17], v[18:19]
	v_add_f32_e32 v18, 1.0, v23
	v_add_f32_e32 v19, 1.0, v56
	v_rcp_f32_e32 v18, v18
	v_rcp_f32_e32 v19, v19
	v_pk_add_f32 v[56:57], v[138:139], v[20:21] op_sel:[0,1] neg_lo:[0,1] neg_hi:[0,1]
	v_pk_add_f32 v[20:21], v[106:107], v[20:21] op_sel:[0,1] neg_lo:[0,1] neg_hi:[0,1]
	v_pk_mul_f32 v[56:57], v[56:57], v[22:23] op_sel_hi:[1,0]
	v_pk_mul_f32 v[18:19], v[18:19], v[30:31]
	v_lshlrev_b32_e32 v30, 16, v58
	v_and_b32_e32 v31, 0xffff0000, v58
	v_mul_f32_e32 v23, 0xbfb8aa3b, v30
	v_exp_f32_e32 v23, v23
	v_mul_f32_e32 v58, 0xbfb8aa3b, v31
	v_exp_f32_e32 v58, v58
	v_pk_mul_f32 v[56:57], v[42:43], v[56:57]
	v_add_f32_e32 v23, 1.0, v23
	v_pk_mul_f32 v[18:19], v[18:19], v[56:57]
	v_rcp_f32_e32 v56, v23
	v_add_f32_e32 v23, 1.0, v58
	v_rcp_f32_e32 v57, v23
	v_pk_mul_f32 v[60:61], v[60:61], v[22:23] op_sel_hi:[1,0]
	v_cvt_pk_bf16_f32 v16, v16, v17
	v_pk_mul_f32 v[60:61], v[32:33], v[60:61]
	v_pk_mul_f32 v[30:31], v[56:57], v[30:31]
	v_lshlrev_b32_e32 v56, 16, v59
	v_and_b32_e32 v57, 0xffff0000, v59
	v_mul_f32_e32 v23, 0xbfb8aa3b, v56
	v_exp_f32_e32 v23, v23
	v_mul_f32_e32 v58, 0xbfb8aa3b, v57
	v_exp_f32_e32 v59, v58
	v_pk_mul_f32 v[30:31], v[30:31], v[60:61]
	v_add_f32_e32 v23, 1.0, v23
	v_rcp_f32_e32 v58, v23
	v_add_f32_e32 v23, 1.0, v59
	v_rcp_f32_e32 v59, v23
	v_pk_mul_f32 v[20:21], v[20:21], v[22:23] op_sel_hi:[1,0]
	v_cvt_pk_bf16_f32 v17, v18, v19
	v_pk_mul_f32 v[20:21], v[34:35], v[20:21]
	v_pk_mul_f32 v[22:23], v[58:59], v[56:57]
	v_cvt_pk_bf16_f32 v18, v30, v31
	v_pk_mul_f32 v[20:21], v[22:23], v[20:21]
	v_add_u32_e32 v60, 0x90, v174
	v_cvt_pk_bf16_f32 v19, v20, v21
	global_store_dwordx4 v[28:29], v[16:19], off offset:256
	ds_read_b32 v17, v152 offset:192
	ds_read_b32 v19, v152 offset:1216
	ds_read_b32 v21, v152 offset:2240
	ds_read_b32 v23, v152 offset:3264
	ds_read_b32 v16, v152 offset:4288
	ds_read_b32 v18, v152 offset:5312
	ds_read_b32 v20, v152 offset:6336
	ds_read_b32 v22, v152 offset:7360
	v_add_u32_e32 v58, 0xa0, v174
	v_add_u32_e32 v56, 0xb0, v174
	s_waitcnt lgkmcnt(0)
	v_pk_add_f32 v[16:17], v[16:17], v[18:19]
	v_ashrrev_i32_e32 v61, 31, v60
	v_pk_add_f32 v[16:17], v[16:17], v[20:21]
	v_lshlrev_b64 v[20:21], 11, v[176:177]
	v_pk_add_f32 v[16:17], v[16:17], v[22:23]
	v_lshlrev_b32_e32 v22, 16, v52
	v_pk_mul_f32 v[16:17], v[16:17], s[16:17] op_sel_hi:[1,0]
	v_and_b32_e32 v23, 0xffff0000, v52
	v_fma_f32 v18, -v17, v17, v16
	v_max_f32_e32 v18, 0, v18
	v_add_f32_e32 v18, 0x358637bd, v18
	v_mul_f32_e32 v19, 0x4b800000, v18
	v_cmp_gt_f32_e32 vcc, s78, v18
	v_mul_f32_e32 v28, 0xbfb8aa3b, v23
	v_exp_f32_e32 v29, v28
	v_cndmask_b32_e32 v18, v18, v19, vcc
	v_rsq_f32_e32 v18, v18
	v_pk_add_f32 v[8:9], v[8:9], v[16:17] op_sel:[0,1] neg_lo:[0,1] neg_hi:[0,1]
	v_pk_add_f32 v[10:11], v[10:11], v[16:17] op_sel:[0,1] neg_lo:[0,1] neg_hi:[0,1]
	v_lshl_add_u64 v[20:21], s[0:1], 0, v[20:21]
	v_mul_f32_e32 v19, 0x45800000, v18
	v_cndmask_b32_e32 v18, v18, v19, vcc
	v_mul_f32_e32 v19, 0xbfb8aa3b, v22
	v_exp_f32_e32 v19, v19
	v_lshl_add_u64 v[20:21], v[20:21], 0, v[86:87]
	v_add_f32_e32 v19, 1.0, v19
	v_rcp_f32_e32 v28, v19
	v_add_f32_e32 v19, 1.0, v29
	v_rcp_f32_e32 v29, v19
	v_pk_mul_f32 v[8:9], v[8:9], v[18:19] op_sel_hi:[1,0]
	v_pk_mul_f32 v[22:23], v[28:29], v[22:23]
	v_lshlrev_b32_e32 v28, 16, v53
	v_and_b32_e32 v29, 0xffff0000, v53
	v_mul_f32_e32 v19, 0xbfb8aa3b, v28
	v_exp_f32_e32 v19, v19
	v_mul_f32_e32 v30, 0xbfb8aa3b, v29
	v_exp_f32_e32 v30, v30
	v_pk_mul_f32 v[8:9], v[44:45], v[8:9]
	v_add_f32_e32 v19, 1.0, v19
	v_pk_mul_f32 v[8:9], v[22:23], v[8:9]
	v_rcp_f32_e32 v22, v19
	v_add_f32_e32 v19, 1.0, v30
	v_rcp_f32_e32 v23, v19
	v_pk_mul_f32 v[10:11], v[10:11], v[18:19] op_sel_hi:[1,0]
	v_cvt_pk_bf16_f32 v8, v8, v9
	v_pk_mul_f32 v[10:11], v[46:47], v[10:11]
	v_pk_mul_f32 v[22:23], v[22:23], v[28:29]
	v_lshlrev_b32_e32 v28, 16, v54
	v_and_b32_e32 v29, 0xffff0000, v54
	v_mul_f32_e32 v19, 0xbfb8aa3b, v28
	v_exp_f32_e32 v19, v19
	v_mul_f32_e32 v30, 0xbfb8aa3b, v29
	v_exp_f32_e32 v30, v30
	v_pk_mul_f32 v[10:11], v[22:23], v[10:11]
	v_add_f32_e32 v19, 1.0, v19
	v_rcp_f32_e32 v22, v19
	v_add_f32_e32 v19, 1.0, v30
	v_rcp_f32_e32 v23, v19
	v_pk_add_f32 v[30:31], v[118:119], v[16:17] op_sel:[0,1] neg_lo:[0,1] neg_hi:[0,1]
	v_cvt_pk_bf16_f32 v9, v10, v11
	v_pk_mul_f32 v[30:31], v[30:31], v[18:19] op_sel_hi:[1,0]
	v_pk_mul_f32 v[22:23], v[22:23], v[28:29]
	v_lshlrev_b32_e32 v28, 16, v55
	v_and_b32_e32 v29, 0xffff0000, v55
	v_mul_f32_e32 v19, 0xbfb8aa3b, v28
	v_exp_f32_e32 v19, v19
	v_mul_f32_e32 v52, 0xbfb8aa3b, v29
	v_exp_f32_e32 v52, v52
	v_pk_mul_f32 v[30:31], v[36:37], v[30:31]
	v_add_f32_e32 v19, 1.0, v19
	v_pk_mul_f32 v[22:23], v[22:23], v[30:31]
	v_rcp_f32_e32 v30, v19
	v_add_f32_e32 v19, 1.0, v52
	v_rcp_f32_e32 v31, v19
	v_pk_add_f32 v[52:53], v[110:111], v[16:17] op_sel:[0,1] neg_lo:[0,1] neg_hi:[0,1]
	v_cvt_pk_bf16_f32 v10, v22, v23
	v_pk_mul_f32 v[52:53], v[52:53], v[18:19] op_sel_hi:[1,0]
	v_pk_mul_f32 v[28:29], v[30:31], v[28:29]
	v_pk_mul_f32 v[52:53], v[38:39], v[52:53]
	v_lshlrev_b32_e32 v22, 16, v48
	v_pk_mul_f32 v[28:29], v[28:29], v[52:53]
	v_and_b32_e32 v23, 0xffff0000, v48
	v_cvt_pk_bf16_f32 v11, v28, v29
	v_mul_f32_e32 v19, 0xbfb8aa3b, v22
	v_mul_f32_e32 v28, 0xbfb8aa3b, v23
	v_exp_f32_e32 v19, v19
	v_exp_f32_e32 v28, v28
	global_store_dwordx4 v[20:21], v[8:11], off
	s_nop 1
	v_add_f32_e32 v8, 1.0, v19
	v_add_f32_e32 v9, 1.0, v28
	v_rcp_f32_e32 v8, v8
	v_rcp_f32_e32 v9, v9
	v_pk_add_f32 v[10:11], v[142:143], v[16:17] op_sel:[0,1] neg_lo:[0,1] neg_hi:[0,1]
	v_pk_mul_f32 v[8:9], v[8:9], v[22:23]
	v_lshlrev_b32_e32 v22, 16, v49
	v_and_b32_e32 v23, 0xffff0000, v49
	v_pk_mul_f32 v[10:11], v[10:11], v[18:19] op_sel_hi:[1,0]
	v_mul_f32_e32 v19, 0xbfb8aa3b, v22
	v_mul_f32_e32 v28, 0xbfb8aa3b, v23
	v_exp_f32_e32 v19, v19
	v_exp_f32_e32 v28, v28
	v_pk_mul_f32 v[10:11], v[40:41], v[10:11]
	s_nop 0
	v_pk_mul_f32 v[8:9], v[8:9], v[10:11]
	v_add_f32_e32 v10, 1.0, v19
	v_add_f32_e32 v11, 1.0, v28
	v_rcp_f32_e32 v10, v10
	v_rcp_f32_e32 v11, v11
	v_pk_add_f32 v[28:29], v[122:123], v[16:17] op_sel:[0,1] neg_lo:[0,1] neg_hi:[0,1]
	v_cvt_pk_bf16_f32 v8, v8, v9
	v_pk_mul_f32 v[28:29], v[28:29], v[18:19] op_sel_hi:[1,0]
	v_pk_mul_f32 v[10:11], v[10:11], v[22:23]
	v_lshlrev_b32_e32 v22, 16, v50
	v_and_b32_e32 v23, 0xffff0000, v50
	v_mul_f32_e32 v19, 0xbfb8aa3b, v22
	v_exp_f32_e32 v19, v19
	v_mul_f32_e32 v30, 0xbfb8aa3b, v23
	v_exp_f32_e32 v30, v30
	v_pk_mul_f32 v[28:29], v[42:43], v[28:29]
	v_add_f32_e32 v19, 1.0, v19
	v_pk_mul_f32 v[10:11], v[10:11], v[28:29]
	v_rcp_f32_e32 v28, v19
	v_add_f32_e32 v19, 1.0, v30
	v_rcp_f32_e32 v29, v19
	v_pk_add_f32 v[30:31], v[108:109], v[16:17] op_sel:[0,1] neg_lo:[0,1] neg_hi:[0,1]
	v_pk_add_f32 v[16:17], v[104:105], v[16:17] op_sel:[0,1] neg_lo:[0,1] neg_hi:[0,1]
	v_pk_mul_f32 v[30:31], v[30:31], v[18:19] op_sel_hi:[1,0]
	v_pk_mul_f32 v[22:23], v[28:29], v[22:23]
	v_lshlrev_b32_e32 v28, 16, v51
	v_and_b32_e32 v29, 0xffff0000, v51
	v_mul_f32_e32 v19, 0xbfb8aa3b, v28
	v_exp_f32_e32 v19, v19
	v_mul_f32_e32 v48, 0xbfb8aa3b, v29
	v_exp_f32_e32 v48, v48
	v_pk_mul_f32 v[30:31], v[32:33], v[30:31]
	v_add_f32_e32 v19, 1.0, v19
	v_pk_mul_f32 v[22:23], v[22:23], v[30:31]
	v_rcp_f32_e32 v30, v19
	v_add_f32_e32 v19, 1.0, v48
	v_rcp_f32_e32 v31, v19
	v_pk_mul_f32 v[16:17], v[16:17], v[18:19] op_sel_hi:[1,0]
	v_cvt_pk_bf16_f32 v9, v10, v11
	v_pk_mul_f32 v[16:17], v[34:35], v[16:17]
	v_pk_mul_f32 v[18:19], v[30:31], v[28:29]
	v_cvt_pk_bf16_f32 v10, v22, v23
	v_pk_mul_f32 v[16:17], v[18:19], v[16:17]
	v_mad_i64_i32 v[104:105], s[2:3], v56, s77, v[172:173]
	v_cvt_pk_bf16_f32 v11, v16, v17
	global_store_dwordx4 v[20:21], v[8:11], off offset:256
	s_nop 1
	v_mad_i64_i32 v[8:9], s[2:3], v70, s77, v[172:173]
	v_lshl_add_u64 v[8:9], v[8:9], 0, v[86:87]
	s_waitcnt vmcnt(8)
	v_mov_b64_e32 v[62:63], v[204:205]
	v_mov_b64_e32 v[64:65], v[206:207]
	v_mov_b64_e32 v[66:67], v[208:209]
	v_mov_b64_e32 v[68:69], v[210:211]
	v_mad_i64_i32 v[8:9], s[2:3], v60, s77, v[172:173]
	v_lshl_add_u64 v[8:9], v[8:9], 0, v[86:87]
	v_mov_b64_e32 v[52:53], v[212:213]
	v_mov_b64_e32 v[54:55], v[214:215]
	v_mov_b64_e32 v[48:49], v[216:217]
	v_mov_b64_e32 v[50:51], v[218:219]
	v_mad_i64_i32 v[8:9], s[2:3], v58, s77, v[172:173]
	v_lshl_add_u64 v[8:9], v[8:9], 0, v[86:87]
	v_mov_b64_e32 v[28:29], v[220:221]
	v_mov_b64_e32 v[30:31], v[222:223]
	v_mov_b64_e32 v[20:21], v[224:225]
	v_mov_b64_e32 v[22:23], v[226:227]
	ds_read_b32 v9, v152 offset:512
	ds_read_b32 v11, v152 offset:1536
	ds_read_b32 v17, v152 offset:2560
	ds_read_b32 v19, v152 offset:3584
	ds_read_b32 v8, v152 offset:4608
	ds_read_b32 v10, v152 offset:5632
	ds_read_b32 v16, v152 offset:6656
	ds_read_b32 v18, v152 offset:7680
	v_lshlrev_b64 v[70:71], 11, v[70:71]
	v_lshl_add_u64 v[70:71], s[0:1], 0, v[70:71]
	s_waitcnt lgkmcnt(0)
	v_pk_add_f32 v[8:9], v[8:9], v[10:11]
	v_lshlrev_b64 v[60:61], 11, v[60:61]
	v_pk_add_f32 v[8:9], v[8:9], v[16:17]
	v_lshl_add_u64 v[60:61], s[0:1], 0, v[60:61]
	v_pk_add_f32 v[8:9], v[8:9], v[18:19]
	v_lshlrev_b32_e32 v108, 16, v62
	v_pk_mul_f32 v[106:107], v[8:9], s[16:17] op_sel_hi:[1,0]
	v_and_b32_e32 v109, 0xffff0000, v62
	v_fma_f32 v8, -v107, v107, v106
	v_max_f32_e32 v8, 0, v8
	v_add_f32_e32 v8, 0x358637bd, v8
	v_mul_f32_e32 v9, 0x4b800000, v8
	v_cmp_gt_f32_e32 vcc, s78, v8
	v_lshlrev_b32_e32 v62, 16, v63
	v_and_b32_e32 v63, 0xffff0000, v63
	v_cndmask_b32_e32 v8, v8, v9, vcc
	v_rsq_f32_e32 v57, v8
	v_lshl_add_u64 v[8:9], v[104:105], 0, v[86:87]
	v_pk_add_f32 v[24:25], v[24:25], v[106:107] op_sel:[0,1] neg_lo:[0,1] neg_hi:[0,1]
	v_pk_add_f32 v[26:27], v[26:27], v[106:107] op_sel:[0,1] neg_lo:[0,1] neg_hi:[0,1]
	v_mul_f32_e32 v59, 0x45800000, v57
	v_cndmask_b32_e32 v104, v57, v59, vcc
	v_mul_f32_e32 v57, 0xbfb8aa3b, v108
	v_exp_f32_e32 v57, v57
	v_mul_f32_e32 v59, 0xbfb8aa3b, v109
	v_exp_f32_e32 v59, v59
	v_pk_mul_f32 v[24:25], v[24:25], v[104:105] op_sel_hi:[1,0]
	v_add_f32_e32 v57, 1.0, v57
	v_rcp_f32_e32 v110, v57
	v_add_f32_e32 v57, 1.0, v59
	v_rcp_f32_e32 v111, v57
	v_mul_f32_e32 v57, 0xbfb8aa3b, v62
	v_exp_f32_e32 v57, v57
	v_mul_f32_e32 v59, 0xbfb8aa3b, v63
	v_exp_f32_e32 v59, v59
	v_pk_mul_f32 v[24:25], v[44:45], v[24:25]
	v_pk_mul_f32 v[108:109], v[110:111], v[108:109]
	v_add_f32_e32 v57, 1.0, v57
	v_pk_mul_f32 v[24:25], v[108:109], v[24:25]
	v_rcp_f32_e32 v108, v57
	v_add_f32_e32 v57, 1.0, v59
	v_rcp_f32_e32 v109, v57
	v_pk_mul_f32 v[26:27], v[26:27], v[104:105] op_sel_hi:[1,0]
	v_pk_add_f32 v[110:111], v[158:159], v[106:107] op_sel:[0,1] neg_lo:[0,1] neg_hi:[0,1]
	v_pk_mul_f32 v[26:27], v[46:47], v[26:27]
	v_pk_mul_f32 v[62:63], v[108:109], v[62:63]
	v_lshlrev_b32_e32 v108, 16, v64
	v_and_b32_e32 v109, 0xffff0000, v64
	v_mul_f32_e32 v57, 0xbfb8aa3b, v108
	v_exp_f32_e32 v57, v57
	v_mul_f32_e32 v59, 0xbfb8aa3b, v109
	v_exp_f32_e32 v59, v59
	v_pk_mul_f32 v[26:27], v[62:63], v[26:27]
	v_add_f32_e32 v57, 1.0, v57
	v_rcp_f32_e32 v62, v57
	v_add_f32_e32 v57, 1.0, v59
	v_lshlrev_b32_e32 v64, 16, v65
	v_rcp_f32_e32 v63, v57
	v_and_b32_e32 v65, 0xffff0000, v65
	v_mul_f32_e32 v57, 0xbfb8aa3b, v64
	v_exp_f32_e32 v57, v57
	v_mul_f32_e32 v59, 0xbfb8aa3b, v65
	v_exp_f32_e32 v59, v59
	v_pk_mul_f32 v[62:63], v[62:63], v[108:109]
	v_add_f32_e32 v57, 1.0, v57
	v_rcp_f32_e32 v108, v57
	v_add_f32_e32 v57, 1.0, v59
	v_pk_mul_f32 v[110:111], v[110:111], v[104:105] op_sel_hi:[1,0]
	v_rcp_f32_e32 v109, v57
	v_pk_mul_f32 v[110:111], v[36:37], v[110:111]
	v_cvt_pk_bf16_f32 v24, v24, v25
	v_pk_mul_f32 v[62:63], v[62:63], v[110:111]
	v_pk_add_f32 v[110:111], v[132:133], v[106:107] op_sel:[0,1] neg_lo:[0,1] neg_hi:[0,1]
	v_pk_mul_f32 v[64:65], v[108:109], v[64:65]
	v_pk_mul_f32 v[110:111], v[110:111], v[104:105] op_sel_hi:[1,0]
	v_cvt_pk_bf16_f32 v25, v26, v27
	v_pk_mul_f32 v[110:111], v[38:39], v[110:111]
	v_cvt_pk_bf16_f32 v26, v62, v63
	v_pk_mul_f32 v[64:65], v[64:65], v[110:111]
	v_lshl_add_u64 v[62:63], v[70:71], 0, v[86:87]
	v_cvt_pk_bf16_f32 v27, v64, v65
	v_lshlrev_b32_e32 v64, 16, v66
	v_and_b32_e32 v65, 0xffff0000, v66
	v_mul_f32_e32 v57, 0xbfb8aa3b, v64
	v_mul_f32_e32 v59, 0xbfb8aa3b, v65
	v_exp_f32_e32 v57, v57
	v_exp_f32_e32 v59, v59
	v_mov_b64_e32 v[16:17], v[228:229]
	v_mov_b64_e32 v[18:19], v[230:231]
	s_nop 0
	v_mov_b64_e32 v[8:9], v[232:233]
	v_mov_b64_e32 v[10:11], v[234:235]
	v_pk_add_f32 v[70:71], v[128:129], v[106:107] op_sel:[0,1] neg_lo:[0,1] neg_hi:[0,1]
	global_store_dwordx4 v[62:63], v[24:27], off
	v_pk_mul_f32 v[70:71], v[70:71], v[104:105] op_sel_hi:[1,0]
	s_nop 0
	v_add_f32_e32 v24, 1.0, v57
	v_add_f32_e32 v25, 1.0, v59
	v_rcp_f32_e32 v24, v24
	v_rcp_f32_e32 v25, v25
	v_pk_add_f32 v[26:27], v[162:163], v[106:107] op_sel:[0,1] neg_lo:[0,1] neg_hi:[0,1]
	v_pk_mul_f32 v[70:71], v[32:33], v[70:71]
	v_pk_mul_f32 v[26:27], v[26:27], v[104:105] op_sel_hi:[1,0]
	v_pk_mul_f32 v[24:25], v[24:25], v[64:65]
	v_lshlrev_b32_e32 v64, 16, v67
	v_and_b32_e32 v65, 0xffff0000, v67
	v_mul_f32_e32 v57, 0xbfb8aa3b, v64
	v_mul_f32_e32 v59, 0xbfb8aa3b, v65
	v_exp_f32_e32 v57, v57
	v_exp_f32_e32 v59, v59
	v_pk_mul_f32 v[26:27], v[40:41], v[26:27]
	v_pk_add_f32 v[66:67], v[146:147], v[106:107] op_sel:[0,1] neg_lo:[0,1] neg_hi:[0,1]
	v_pk_mul_f32 v[24:25], v[24:25], v[26:27]
	v_add_f32_e32 v26, 1.0, v57
	v_add_f32_e32 v27, 1.0, v59
	v_rcp_f32_e32 v26, v26
	v_rcp_f32_e32 v27, v27
	v_pk_mul_f32 v[66:67], v[66:67], v[104:105] op_sel_hi:[1,0]
	v_cvt_pk_bf16_f32 v24, v24, v25
	v_pk_mul_f32 v[66:67], v[42:43], v[66:67]
	v_pk_mul_f32 v[26:27], v[26:27], v[64:65]
	v_lshlrev_b32_e32 v64, 16, v68
	v_and_b32_e32 v65, 0xffff0000, v68
	v_mul_f32_e32 v57, 0xbfb8aa3b, v64
	v_exp_f32_e32 v57, v57
	v_mul_f32_e32 v59, 0xbfb8aa3b, v65
	v_exp_f32_e32 v59, v59
	v_pk_mul_f32 v[26:27], v[26:27], v[66:67]
	v_add_f32_e32 v57, 1.0, v57
	v_rcp_f32_e32 v66, v57
	v_add_f32_e32 v57, 1.0, v59
	v_rcp_f32_e32 v67, v57
	v_cvt_pk_bf16_f32 v25, v26, v27
	v_pk_mul_f32 v[64:65], v[66:67], v[64:65]
	v_lshlrev_b32_e32 v66, 16, v69
	v_and_b32_e32 v67, 0xffff0000, v69
	v_mul_f32_e32 v57, 0xbfb8aa3b, v66
	v_exp_f32_e32 v57, v57
	v_mul_f32_e32 v59, 0xbfb8aa3b, v67
	v_exp_f32_e32 v59, v59
	v_pk_mul_f32 v[64:65], v[64:65], v[70:71]
	v_add_f32_e32 v57, 1.0, v57
	v_rcp_f32_e32 v68, v57
	v_add_f32_e32 v57, 1.0, v59
	v_rcp_f32_e32 v69, v57
	v_pk_add_f32 v[70:71], v[112:113], v[106:107] op_sel:[0,1] neg_lo:[0,1] neg_hi:[0,1]
	v_cvt_pk_bf16_f32 v26, v64, v65
	v_pk_mul_f32 v[70:71], v[70:71], v[104:105] op_sel_hi:[1,0]
	v_pk_mul_f32 v[66:67], v[68:69], v[66:67]
	v_pk_mul_f32 v[70:71], v[34:35], v[70:71]
	v_ashrrev_i32_e32 v59, 31, v58
	v_pk_mul_f32 v[66:67], v[66:67], v[70:71]
	s_nop 0
	v_cvt_pk_bf16_f32 v27, v66, v67
	global_store_dwordx4 v[62:63], v[24:27], off offset:256
	ds_read_b32 v25, v152 offset:576
	ds_read_b32 v27, v152 offset:1600
	ds_read_b32 v63, v152 offset:2624
	ds_read_b32 v65, v152 offset:3648
	ds_read_b32 v24, v152 offset:4672
	ds_read_b32 v26, v152 offset:5696
	ds_read_b32 v62, v152 offset:6720
	ds_read_b32 v64, v152 offset:7744
	s_waitcnt lgkmcnt(0)
	v_pk_add_f32 v[24:25], v[24:25], v[26:27]
	s_nop 0
	v_pk_add_f32 v[24:25], v[24:25], v[62:63]
	v_lshlrev_b32_e32 v62, 16, v52
	v_pk_add_f32 v[24:25], v[24:25], v[64:65]
	v_and_b32_e32 v63, 0xffff0000, v52
	v_pk_mul_f32 v[24:25], v[24:25], s[16:17] op_sel_hi:[1,0]
	v_mul_f32_e32 v52, 0xbfb8aa3b, v63
	v_fma_f32 v26, -v25, v25, v24
	v_max_f32_e32 v26, 0, v26
	v_add_f32_e32 v26, 0x358637bd, v26
	v_mul_f32_e32 v27, 0x4b800000, v26
	v_cmp_gt_f32_e32 vcc, s78, v26
	v_exp_f32_e32 v52, v52
	v_pk_add_f32 v[12:13], v[12:13], v[24:25] op_sel:[0,1] neg_lo:[0,1] neg_hi:[0,1]
	v_cndmask_b32_e32 v26, v26, v27, vcc
	v_rsq_f32_e32 v26, v26
	v_pk_add_f32 v[14:15], v[14:15], v[24:25] op_sel:[0,1] neg_lo:[0,1] neg_hi:[0,1]
	v_mul_f32_e32 v27, 0x45800000, v26
	v_cndmask_b32_e32 v26, v26, v27, vcc
	v_mul_f32_e32 v27, 0xbfb8aa3b, v62
	v_exp_f32_e32 v27, v27
	s_nop 0
	v_add_f32_e32 v27, 1.0, v27
	v_rcp_f32_e32 v64, v27
	v_add_f32_e32 v27, 1.0, v52
	v_lshlrev_b32_e32 v52, 16, v53
	v_rcp_f32_e32 v65, v27
	v_pk_mul_f32 v[12:13], v[12:13], v[26:27] op_sel_hi:[1,0]
	v_and_b32_e32 v53, 0xffff0000, v53
	v_mul_f32_e32 v27, 0xbfb8aa3b, v52
	v_exp_f32_e32 v27, v27
	v_mul_f32_e32 v57, 0xbfb8aa3b, v53
	v_exp_f32_e32 v57, v57
	v_pk_mul_f32 v[12:13], v[44:45], v[12:13]
	v_pk_mul_f32 v[62:63], v[64:65], v[62:63]
	v_add_f32_e32 v27, 1.0, v27
	v_pk_mul_f32 v[12:13], v[62:63], v[12:13]
	v_rcp_f32_e32 v62, v27
	v_add_f32_e32 v27, 1.0, v57
	v_rcp_f32_e32 v63, v27
	v_pk_mul_f32 v[14:15], v[14:15], v[26:27] op_sel_hi:[1,0]
	v_pk_add_f32 v[64:65], v[124:125], v[24:25] op_sel:[0,1] neg_lo:[0,1] neg_hi:[0,1]
	v_pk_mul_f32 v[14:15], v[46:47], v[14:15]
	v_pk_mul_f32 v[52:53], v[62:63], v[52:53]
	v_lshlrev_b32_e32 v62, 16, v54
	v_and_b32_e32 v63, 0xffff0000, v54
	v_mul_f32_e32 v27, 0xbfb8aa3b, v62
	v_exp_f32_e32 v27, v27
	v_mul_f32_e32 v54, 0xbfb8aa3b, v63
	v_exp_f32_e32 v54, v54
	v_pk_mul_f32 v[14:15], v[52:53], v[14:15]
	v_add_f32_e32 v27, 1.0, v27
	v_rcp_f32_e32 v52, v27
	v_add_f32_e32 v27, 1.0, v54
	v_lshlrev_b32_e32 v54, 16, v55
	v_rcp_f32_e32 v53, v27
	v_pk_mul_f32 v[64:65], v[64:65], v[26:27] op_sel_hi:[1,0]
	v_and_b32_e32 v55, 0xffff0000, v55
	v_mul_f32_e32 v27, 0xbfb8aa3b, v54
	v_exp_f32_e32 v27, v27
	v_mul_f32_e32 v57, 0xbfb8aa3b, v55
	v_exp_f32_e32 v57, v57
	v_pk_mul_f32 v[52:53], v[52:53], v[62:63]
	v_add_f32_e32 v27, 1.0, v27
	v_rcp_f32_e32 v62, v27
	v_add_f32_e32 v27, 1.0, v57
	v_rcp_f32_e32 v63, v27
	v_pk_mul_f32 v[64:65], v[36:37], v[64:65]
	v_cvt_pk_bf16_f32 v12, v12, v13
	v_pk_mul_f32 v[52:53], v[52:53], v[64:65]
	v_pk_add_f32 v[64:65], v[100:101], v[24:25] op_sel:[0,1] neg_lo:[0,1] neg_hi:[0,1]
	v_pk_mul_f32 v[54:55], v[62:63], v[54:55]
	v_pk_mul_f32 v[64:65], v[64:65], v[26:27] op_sel_hi:[1,0]
	v_cvt_pk_bf16_f32 v13, v14, v15
	v_pk_mul_f32 v[64:65], v[38:39], v[64:65]
	v_cvt_pk_bf16_f32 v14, v52, v53
	v_pk_mul_f32 v[54:55], v[54:55], v[64:65]
	v_lshl_add_u64 v[52:53], v[60:61], 0, v[86:87]
	v_cvt_pk_bf16_f32 v15, v54, v55
	v_lshlrev_b32_e32 v54, 16, v48
	v_and_b32_e32 v55, 0xffff0000, v48
	v_mul_f32_e32 v27, 0xbfb8aa3b, v54
	v_mul_f32_e32 v48, 0xbfb8aa3b, v55
	v_exp_f32_e32 v27, v27
	v_exp_f32_e32 v48, v48
	global_store_dwordx4 v[52:53], v[12:15], off
	v_pk_add_f32 v[60:61], v[98:99], v[24:25] op_sel:[0,1] neg_lo:[0,1] neg_hi:[0,1]
	v_ashrrev_i32_e32 v57, 31, v56
	v_add_f32_e32 v12, 1.0, v27
	v_add_f32_e32 v13, 1.0, v48
	v_rcp_f32_e32 v12, v12
	v_rcp_f32_e32 v13, v13
	v_pk_add_f32 v[14:15], v[144:145], v[24:25] op_sel:[0,1] neg_lo:[0,1] neg_hi:[0,1]
	v_lshlrev_b32_e32 v48, 16, v49
	v_and_b32_e32 v49, 0xffff0000, v49
	v_pk_mul_f32 v[14:15], v[14:15], v[26:27] op_sel_hi:[1,0]
	v_pk_mul_f32 v[12:13], v[12:13], v[54:55]
	v_mul_f32_e32 v27, 0xbfb8aa3b, v48
	v_mul_f32_e32 v54, 0xbfb8aa3b, v49
	v_exp_f32_e32 v27, v27
	v_exp_f32_e32 v54, v54
	v_pk_mul_f32 v[14:15], v[40:41], v[14:15]
	s_nop 0
	v_pk_mul_f32 v[12:13], v[12:13], v[14:15]
	v_add_f32_e32 v14, 1.0, v27
	v_add_f32_e32 v15, 1.0, v54
	v_rcp_f32_e32 v14, v14
	v_rcp_f32_e32 v15, v15
	v_pk_add_f32 v[54:55], v[126:127], v[24:25] op_sel:[0,1] neg_lo:[0,1] neg_hi:[0,1]
	v_pk_add_f32 v[24:25], v[96:97], v[24:25] op_sel:[0,1] neg_lo:[0,1] neg_hi:[0,1]
	v_pk_mul_f32 v[54:55], v[54:55], v[26:27] op_sel_hi:[1,0]
	v_pk_mul_f32 v[14:15], v[14:15], v[48:49]
	v_lshlrev_b32_e32 v48, 16, v50
	v_and_b32_e32 v49, 0xffff0000, v50
	v_mul_f32_e32 v27, 0xbfb8aa3b, v48
	v_exp_f32_e32 v27, v27
	v_mul_f32_e32 v50, 0xbfb8aa3b, v49
	v_exp_f32_e32 v50, v50
	v_pk_mul_f32 v[54:55], v[42:43], v[54:55]
	v_add_f32_e32 v27, 1.0, v27
	v_pk_mul_f32 v[14:15], v[14:15], v[54:55]
	v_rcp_f32_e32 v54, v27
	v_add_f32_e32 v27, 1.0, v50
	v_rcp_f32_e32 v55, v27
	v_lshlrev_b32_e32 v50, 16, v51
	v_pk_mul_f32 v[60:61], v[60:61], v[26:27] op_sel_hi:[1,0]
	v_and_b32_e32 v51, 0xffff0000, v51
	v_mul_f32_e32 v27, 0xbfb8aa3b, v50
	v_pk_mul_f32 v[48:49], v[54:55], v[48:49]
	v_exp_f32_e32 v27, v27
	v_mul_f32_e32 v54, 0xbfb8aa3b, v51
	v_exp_f32_e32 v55, v54
	v_pk_mul_f32 v[60:61], v[32:33], v[60:61]
	v_add_f32_e32 v27, 1.0, v27
	v_rcp_f32_e32 v54, v27
	v_add_f32_e32 v27, 1.0, v55
	v_rcp_f32_e32 v55, v27
	v_pk_mul_f32 v[24:25], v[24:25], v[26:27] op_sel_hi:[1,0]
	v_pk_mul_f32 v[48:49], v[48:49], v[60:61]
	v_pk_mul_f32 v[24:25], v[34:35], v[24:25]
	v_pk_mul_f32 v[26:27], v[54:55], v[50:51]
	v_cvt_pk_bf16_f32 v12, v12, v13
	v_pk_mul_f32 v[24:25], v[26:27], v[24:25]
	v_cvt_pk_bf16_f32 v13, v14, v15
	v_cvt_pk_bf16_f32 v14, v48, v49
	v_cvt_pk_bf16_f32 v15, v24, v25
	global_store_dwordx4 v[52:53], v[12:15], off offset:256
	ds_read_b32 v13, v152 offset:640
	ds_read_b32 v15, v152 offset:1664
	ds_read_b32 v25, v152 offset:2688
	ds_read_b32 v27, v152 offset:3712
	ds_read_b32 v12, v152 offset:4736
	ds_read_b32 v14, v152 offset:5760
	ds_read_b32 v24, v152 offset:6784
	ds_read_b32 v26, v152 offset:7808
	s_waitcnt lgkmcnt(0)
	v_pk_add_f32 v[12:13], v[12:13], v[14:15]
	s_nop 0
	v_pk_add_f32 v[12:13], v[12:13], v[24:25]
	v_lshlrev_b64 v[24:25], 11, v[58:59]
	v_pk_add_f32 v[12:13], v[12:13], v[26:27]
	v_lshlrev_b32_e32 v26, 16, v28
	v_pk_mul_f32 v[12:13], v[12:13], s[16:17] op_sel_hi:[1,0]
	v_and_b32_e32 v27, 0xffff0000, v28
	v_fma_f32 v14, -v13, v13, v12
	v_max_f32_e32 v14, 0, v14
	v_add_f32_e32 v14, 0x358637bd, v14
	v_mul_f32_e32 v15, 0x4b800000, v14
	v_cmp_gt_f32_e32 vcc, s78, v14
	v_mul_f32_e32 v28, 0xbfb8aa3b, v27
	v_exp_f32_e32 v28, v28
	v_cndmask_b32_e32 v14, v14, v15, vcc
	v_rsq_f32_e32 v14, v14
	v_pk_add_f32 v[4:5], v[4:5], v[12:13] op_sel:[0,1] neg_lo:[0,1] neg_hi:[0,1]
	v_pk_add_f32 v[6:7], v[6:7], v[12:13] op_sel:[0,1] neg_lo:[0,1] neg_hi:[0,1]
	v_lshl_add_u64 v[24:25], s[0:1], 0, v[24:25]
	v_mul_f32_e32 v15, 0x45800000, v14
	v_cndmask_b32_e32 v14, v14, v15, vcc
	v_mul_f32_e32 v15, 0xbfb8aa3b, v26
	v_exp_f32_e32 v15, v15
	v_lshl_add_u64 v[24:25], v[24:25], 0, v[86:87]
	v_add_f32_e32 v15, 1.0, v15
	v_rcp_f32_e32 v48, v15
	v_add_f32_e32 v15, 1.0, v28
	v_rcp_f32_e32 v49, v15
	v_lshlrev_b32_e32 v28, 16, v29
	v_pk_mul_f32 v[4:5], v[4:5], v[14:15] op_sel_hi:[1,0]
	v_and_b32_e32 v29, 0xffff0000, v29
	v_mul_f32_e32 v15, 0xbfb8aa3b, v28
	v_pk_mul_f32 v[26:27], v[48:49], v[26:27]
	v_exp_f32_e32 v15, v15
	v_mul_f32_e32 v48, 0xbfb8aa3b, v29
	v_exp_f32_e32 v48, v48
	v_pk_mul_f32 v[4:5], v[44:45], v[4:5]
	v_add_f32_e32 v15, 1.0, v15
	v_pk_mul_f32 v[4:5], v[26:27], v[4:5]
	v_rcp_f32_e32 v26, v15
	v_add_f32_e32 v15, 1.0, v48
	v_rcp_f32_e32 v27, v15
	v_pk_mul_f32 v[6:7], v[6:7], v[14:15] op_sel_hi:[1,0]
	v_pk_add_f32 v[48:49], v[94:95], v[12:13] op_sel:[0,1] neg_lo:[0,1] neg_hi:[0,1]
	v_pk_mul_f32 v[6:7], v[46:47], v[6:7]
	v_pk_mul_f32 v[26:27], v[26:27], v[28:29]
	v_lshlrev_b32_e32 v28, 16, v30
	v_and_b32_e32 v29, 0xffff0000, v30
	v_mul_f32_e32 v15, 0xbfb8aa3b, v28
	v_exp_f32_e32 v15, v15
	v_mul_f32_e32 v30, 0xbfb8aa3b, v29
	v_exp_f32_e32 v30, v30
	v_pk_mul_f32 v[6:7], v[26:27], v[6:7]
	v_add_f32_e32 v15, 1.0, v15
	v_rcp_f32_e32 v26, v15
	v_add_f32_e32 v15, 1.0, v30
	v_rcp_f32_e32 v27, v15
	v_pk_mul_f32 v[48:49], v[48:49], v[14:15] op_sel_hi:[1,0]
	v_cvt_pk_bf16_f32 v4, v4, v5
	v_pk_mul_f32 v[48:49], v[36:37], v[48:49]
	v_pk_mul_f32 v[26:27], v[26:27], v[28:29]
	v_lshlrev_b32_e32 v28, 16, v31
	v_and_b32_e32 v29, 0xffff0000, v31
	v_mul_f32_e32 v15, 0xbfb8aa3b, v28
	v_exp_f32_e32 v15, v15
	v_mul_f32_e32 v30, 0xbfb8aa3b, v29
	v_exp_f32_e32 v31, v30
	v_pk_mul_f32 v[26:27], v[26:27], v[48:49]
	v_add_f32_e32 v15, 1.0, v15
	v_rcp_f32_e32 v30, v15
	v_add_f32_e32 v15, 1.0, v31
	v_rcp_f32_e32 v31, v15
	v_pk_add_f32 v[48:49], v[92:93], v[12:13] op_sel:[0,1] neg_lo:[0,1] neg_hi:[0,1]
	v_cvt_pk_bf16_f32 v5, v6, v7
	v_cvt_pk_bf16_f32 v6, v26, v27
	v_lshlrev_b32_e32 v26, 16, v20
	v_and_b32_e32 v27, 0xffff0000, v20
	v_pk_mul_f32 v[48:49], v[48:49], v[14:15] op_sel_hi:[1,0]
	v_mul_f32_e32 v15, 0xbfb8aa3b, v26
	v_mul_f32_e32 v20, 0xbfb8aa3b, v27
	v_exp_f32_e32 v15, v15
	v_exp_f32_e32 v20, v20
	v_pk_mul_f32 v[48:49], v[38:39], v[48:49]
	v_pk_mul_f32 v[28:29], v[30:31], v[28:29]
	s_nop 0
	v_pk_mul_f32 v[28:29], v[28:29], v[48:49]
	s_nop 0
	v_cvt_pk_bf16_f32 v7, v28, v29
	global_store_dwordx4 v[24:25], v[4:7], off
	v_pk_add_f32 v[28:29], v[88:89], v[12:13] op_sel:[0,1] neg_lo:[0,1] neg_hi:[0,1]
	s_nop 0
	v_add_f32_e32 v4, 1.0, v15
	v_add_f32_e32 v5, 1.0, v20
	v_rcp_f32_e32 v4, v4
	v_rcp_f32_e32 v5, v5
	v_pk_add_f32 v[6:7], v[102:103], v[12:13] op_sel:[0,1] neg_lo:[0,1] neg_hi:[0,1]
	v_lshlrev_b32_e32 v20, 16, v21
	v_and_b32_e32 v21, 0xffff0000, v21
	v_pk_mul_f32 v[6:7], v[6:7], v[14:15] op_sel_hi:[1,0]
	v_pk_mul_f32 v[4:5], v[4:5], v[26:27]
	v_mul_f32_e32 v15, 0xbfb8aa3b, v20
	v_mul_f32_e32 v26, 0xbfb8aa3b, v21
	v_exp_f32_e32 v15, v15
	v_exp_f32_e32 v26, v26
	v_pk_mul_f32 v[6:7], v[40:41], v[6:7]
	s_nop 0
	v_pk_mul_f32 v[4:5], v[4:5], v[6:7]
	v_add_f32_e32 v6, 1.0, v15
	v_add_f32_e32 v7, 1.0, v26
	v_rcp_f32_e32 v6, v6
	v_rcp_f32_e32 v7, v7
	v_pk_add_f32 v[26:27], v[90:91], v[12:13] op_sel:[0,1] neg_lo:[0,1] neg_hi:[0,1]
	v_pk_add_f32 v[12:13], v[78:79], v[12:13] op_sel:[0,1] neg_lo:[0,1] neg_hi:[0,1]
	v_pk_mul_f32 v[26:27], v[26:27], v[14:15] op_sel_hi:[1,0]
	v_pk_mul_f32 v[6:7], v[6:7], v[20:21]
	v_lshlrev_b32_e32 v20, 16, v22
	v_and_b32_e32 v21, 0xffff0000, v22
	v_mul_f32_e32 v15, 0xbfb8aa3b, v20
	v_exp_f32_e32 v15, v15
	v_mul_f32_e32 v22, 0xbfb8aa3b, v21
	v_exp_f32_e32 v22, v22
	v_pk_mul_f32 v[26:27], v[42:43], v[26:27]
	v_add_f32_e32 v15, 1.0, v15
	v_pk_mul_f32 v[6:7], v[6:7], v[26:27]
	v_rcp_f32_e32 v26, v15
	v_add_f32_e32 v15, 1.0, v22
	v_rcp_f32_e32 v27, v15
	v_lshlrev_b32_e32 v22, 16, v23
	v_pk_mul_f32 v[28:29], v[28:29], v[14:15] op_sel_hi:[1,0]
	v_and_b32_e32 v23, 0xffff0000, v23
	v_mul_f32_e32 v15, 0xbfb8aa3b, v22
	v_pk_mul_f32 v[20:21], v[26:27], v[20:21]
	v_exp_f32_e32 v15, v15
	v_mul_f32_e32 v26, 0xbfb8aa3b, v23
	v_exp_f32_e32 v27, v26
	v_pk_mul_f32 v[28:29], v[32:33], v[28:29]
	v_add_f32_e32 v15, 1.0, v15
	v_rcp_f32_e32 v26, v15
	v_add_f32_e32 v15, 1.0, v27
	v_rcp_f32_e32 v27, v15
	v_pk_mul_f32 v[12:13], v[12:13], v[14:15] op_sel_hi:[1,0]
	v_pk_mul_f32 v[20:21], v[20:21], v[28:29]
	v_pk_mul_f32 v[12:13], v[34:35], v[12:13]
	v_pk_mul_f32 v[14:15], v[26:27], v[22:23]
	v_cvt_pk_bf16_f32 v4, v4, v5
	v_pk_mul_f32 v[12:13], v[14:15], v[12:13]
	v_cvt_pk_bf16_f32 v5, v6, v7
	v_cvt_pk_bf16_f32 v6, v20, v21
	v_cvt_pk_bf16_f32 v7, v12, v13
	global_store_dwordx4 v[24:25], v[4:7], off offset:256
	ds_read_b32 v5, v152 offset:704
	ds_read_b32 v7, v152 offset:1728
	ds_read_b32 v13, v152 offset:2752
	ds_read_b32 v15, v152 offset:3776
	ds_read_b32 v4, v152 offset:4800
	ds_read_b32 v6, v152 offset:5824
	ds_read_b32 v12, v152 offset:6848
	ds_read_b32 v14, v152 offset:7872
	s_waitcnt lgkmcnt(0)
	v_pk_add_f32 v[4:5], v[4:5], v[6:7]
	s_nop 0
	v_pk_add_f32 v[4:5], v[4:5], v[12:13]
	v_lshlrev_b64 v[12:13], 11, v[56:57]
	v_pk_add_f32 v[4:5], v[4:5], v[14:15]
	v_lshlrev_b32_e32 v14, 16, v16
	v_pk_mul_f32 v[4:5], v[4:5], s[16:17] op_sel_hi:[1,0]
	v_and_b32_e32 v15, 0xffff0000, v16
	v_fma_f32 v6, -v5, v5, v4
	v_max_f32_e32 v6, 0, v6
	v_add_f32_e32 v6, 0x358637bd, v6
	v_mul_f32_e32 v7, 0x4b800000, v6
	v_cmp_gt_f32_e32 vcc, s78, v6
	v_mul_f32_e32 v16, 0xbfb8aa3b, v15
	v_exp_f32_e32 v16, v16
	v_cndmask_b32_e32 v6, v6, v7, vcc
	v_rsq_f32_e32 v6, v6
	v_pk_add_f32 v[0:1], v[0:1], v[4:5] op_sel:[0,1] neg_lo:[0,1] neg_hi:[0,1]
	v_pk_add_f32 v[2:3], v[2:3], v[4:5] op_sel:[0,1] neg_lo:[0,1] neg_hi:[0,1]
	v_lshl_add_u64 v[12:13], s[0:1], 0, v[12:13]
	v_mul_f32_e32 v7, 0x45800000, v6
	v_cndmask_b32_e32 v6, v6, v7, vcc
	v_mul_f32_e32 v7, 0xbfb8aa3b, v14
	v_exp_f32_e32 v7, v7
	v_lshl_add_u64 v[12:13], v[12:13], 0, v[86:87]
	v_add_f32_e32 v7, 1.0, v7
	v_rcp_f32_e32 v20, v7
	v_add_f32_e32 v7, 1.0, v16
	v_rcp_f32_e32 v21, v7
	v_lshlrev_b32_e32 v16, 16, v17
	v_pk_mul_f32 v[0:1], v[0:1], v[6:7] op_sel_hi:[1,0]
	v_and_b32_e32 v17, 0xffff0000, v17
	v_mul_f32_e32 v7, 0xbfb8aa3b, v16
	v_pk_mul_f32 v[14:15], v[20:21], v[14:15]
	v_exp_f32_e32 v7, v7
	v_mul_f32_e32 v20, 0xbfb8aa3b, v17
	v_exp_f32_e32 v20, v20
	v_pk_mul_f32 v[0:1], v[44:45], v[0:1]
	v_add_f32_e32 v7, 1.0, v7
	v_pk_mul_f32 v[0:1], v[14:15], v[0:1]
	v_rcp_f32_e32 v14, v7
	v_add_f32_e32 v7, 1.0, v20
	v_rcp_f32_e32 v15, v7
	v_pk_mul_f32 v[2:3], v[2:3], v[6:7] op_sel_hi:[1,0]
	v_pk_add_f32 v[20:21], v[84:85], v[4:5] op_sel:[0,1] neg_lo:[0,1] neg_hi:[0,1]
	v_pk_mul_f32 v[2:3], v[46:47], v[2:3]
	v_pk_mul_f32 v[14:15], v[14:15], v[16:17]
	v_lshlrev_b32_e32 v16, 16, v18
	v_and_b32_e32 v17, 0xffff0000, v18
	v_mul_f32_e32 v7, 0xbfb8aa3b, v16
	v_exp_f32_e32 v7, v7
	v_mul_f32_e32 v18, 0xbfb8aa3b, v17
	v_exp_f32_e32 v18, v18
	v_pk_mul_f32 v[2:3], v[14:15], v[2:3]
	v_add_f32_e32 v7, 1.0, v7
	v_rcp_f32_e32 v14, v7
	v_add_f32_e32 v7, 1.0, v18
	v_rcp_f32_e32 v15, v7
	v_pk_mul_f32 v[20:21], v[20:21], v[6:7] op_sel_hi:[1,0]
	v_cvt_pk_bf16_f32 v0, v0, v1
	v_pk_mul_f32 v[20:21], v[36:37], v[20:21]
	v_pk_mul_f32 v[14:15], v[14:15], v[16:17]
	v_lshlrev_b32_e32 v16, 16, v19
	v_and_b32_e32 v17, 0xffff0000, v19
	v_mul_f32_e32 v7, 0xbfb8aa3b, v16
	v_exp_f32_e32 v7, v7
	v_mul_f32_e32 v18, 0xbfb8aa3b, v17
	v_exp_f32_e32 v19, v18
	v_pk_mul_f32 v[14:15], v[14:15], v[20:21]
	v_add_f32_e32 v7, 1.0, v7
	v_rcp_f32_e32 v18, v7
	v_add_f32_e32 v7, 1.0, v19
	v_rcp_f32_e32 v19, v7
	v_pk_add_f32 v[20:21], v[76:77], v[4:5] op_sel:[0,1] neg_lo:[0,1] neg_hi:[0,1]
	v_cvt_pk_bf16_f32 v1, v2, v3
	v_cvt_pk_bf16_f32 v2, v14, v15
	v_lshlrev_b32_e32 v14, 16, v8
	v_and_b32_e32 v15, 0xffff0000, v8
	v_pk_mul_f32 v[20:21], v[20:21], v[6:7] op_sel_hi:[1,0]
	v_mul_f32_e32 v7, 0xbfb8aa3b, v14
	v_mul_f32_e32 v8, 0xbfb8aa3b, v15
	v_exp_f32_e32 v7, v7
	v_exp_f32_e32 v8, v8
	v_pk_mul_f32 v[20:21], v[38:39], v[20:21]
	v_pk_mul_f32 v[16:17], v[18:19], v[16:17]
	s_nop 0
	v_pk_mul_f32 v[16:17], v[16:17], v[20:21]
	s_nop 0
	v_cvt_pk_bf16_f32 v3, v16, v17
	global_store_dwordx4 v[12:13], v[0:3], off
	v_pk_add_f32 v[16:17], v[74:75], v[4:5] op_sel:[0,1] neg_lo:[0,1] neg_hi:[0,1]
	s_nop 0
	v_add_f32_e32 v0, 1.0, v7
	v_add_f32_e32 v1, 1.0, v8
	v_rcp_f32_e32 v0, v0
	v_rcp_f32_e32 v1, v1
	v_pk_add_f32 v[2:3], v[82:83], v[4:5] op_sel:[0,1] neg_lo:[0,1] neg_hi:[0,1]
	v_lshlrev_b32_e32 v8, 16, v9
	v_and_b32_e32 v9, 0xffff0000, v9
	v_pk_mul_f32 v[2:3], v[2:3], v[6:7] op_sel_hi:[1,0]
	v_pk_mul_f32 v[0:1], v[0:1], v[14:15]
	v_mul_f32_e32 v7, 0xbfb8aa3b, v8
	v_mul_f32_e32 v14, 0xbfb8aa3b, v9
	v_exp_f32_e32 v7, v7
	v_exp_f32_e32 v14, v14
	v_pk_mul_f32 v[2:3], v[40:41], v[2:3]
	s_nop 0
	v_pk_mul_f32 v[0:1], v[0:1], v[2:3]
	v_add_f32_e32 v2, 1.0, v7
	v_add_f32_e32 v3, 1.0, v14
	v_rcp_f32_e32 v2, v2
	v_rcp_f32_e32 v3, v3
	v_pk_add_f32 v[14:15], v[80:81], v[4:5] op_sel:[0,1] neg_lo:[0,1] neg_hi:[0,1]
	v_pk_add_f32 v[4:5], v[72:73], v[4:5] op_sel:[0,1] neg_lo:[0,1] neg_hi:[0,1]
	v_pk_mul_f32 v[14:15], v[14:15], v[6:7] op_sel_hi:[1,0]
	v_pk_mul_f32 v[2:3], v[2:3], v[8:9]
	v_lshlrev_b32_e32 v8, 16, v10
	v_and_b32_e32 v9, 0xffff0000, v10
	v_mul_f32_e32 v7, 0xbfb8aa3b, v8
	v_exp_f32_e32 v7, v7
	v_mul_f32_e32 v10, 0xbfb8aa3b, v9
	v_exp_f32_e32 v10, v10
	v_pk_mul_f32 v[14:15], v[42:43], v[14:15]
	v_add_f32_e32 v7, 1.0, v7
	v_pk_mul_f32 v[2:3], v[2:3], v[14:15]
	v_rcp_f32_e32 v14, v7
	v_add_f32_e32 v7, 1.0, v10
	v_rcp_f32_e32 v15, v7
	v_lshlrev_b32_e32 v10, 16, v11
	v_pk_mul_f32 v[16:17], v[16:17], v[6:7] op_sel_hi:[1,0]
	v_and_b32_e32 v11, 0xffff0000, v11
	v_mul_f32_e32 v7, 0xbfb8aa3b, v10
	v_pk_mul_f32 v[8:9], v[14:15], v[8:9]
	v_exp_f32_e32 v7, v7
	v_mul_f32_e32 v14, 0xbfb8aa3b, v11
	v_exp_f32_e32 v15, v14
	v_pk_mul_f32 v[16:17], v[32:33], v[16:17]
	v_add_f32_e32 v7, 1.0, v7
	v_rcp_f32_e32 v14, v7
	v_add_f32_e32 v7, 1.0, v15
	v_rcp_f32_e32 v15, v7
	v_pk_mul_f32 v[4:5], v[4:5], v[6:7] op_sel_hi:[1,0]
	v_pk_mul_f32 v[8:9], v[8:9], v[16:17]
	v_pk_mul_f32 v[4:5], v[34:35], v[4:5]
	v_pk_mul_f32 v[6:7], v[14:15], v[10:11]
	v_cvt_pk_bf16_f32 v0, v0, v1
	v_pk_mul_f32 v[4:5], v[6:7], v[4:5]
	v_cvt_pk_bf16_f32 v1, v2, v3
	v_cvt_pk_bf16_f32 v2, v8, v9
	v_cvt_pk_bf16_f32 v3, v4, v5
	global_store_dwordx4 v[12:13], v[0:3], off offset:256
	s_cbranch_scc1 .LBB0_679

.LBB0_663:
	s_mov_b64 s[98:99], 0xc0000
	s_lshl_b32 s2, s33, 8
	s_mul_i32 s1, s20, 0x1800
	s_mul_hi_i32 s0, s20, 0x1800
	s_add_u32 s24, s58, s1
	v_mov_b32_e32 v92, v182
	s_addc_u32 s25, s59, s0
	s_lshl_b32 s19, s2, 1
	s_add_u32 s0, s24, s19
	v_and_b32_e32 v155, 63, v92
	s_addc_u32 s1, s25, 0
	v_ashrrev_i32_e32 v92, 1, v155
	s_add_u32 s0, s0, 0x8800800
	v_and_b32_e32 v92, -8, v92
	s_addc_u32 s1, s1, 0
	v_add_u32_e32 v92, s80, v92
	v_and_or_b32 v162, v155, 15, s79
	v_ashrrev_i32_e32 v93, 31, v92
	v_mov_b64_e32 v[94:95], s[0:1]
	v_mad_i64_i32 v[96:97], s[22:23], v162, s77, v[94:95]
	v_lshlrev_b64 v[158:159], 1, v[92:93]
	v_lshl_add_u64 v[92:93], v[96:97], 0, v[158:159]
	v_lshl_add_u64 v[232:233], v[92:93], 0, s[98:99]
	global_load_dwordx4 v[164:167], v[92:93], off nt
	v_lshl_add_u32 v96, v162, 2, 0
	v_add_u32_e32 v152, 0x21400, v96
	v_add_u32_e32 v174, 0x20400, v96
	v_add_u32_e32 v175, 0x21000, v96
	v_add_u32_e32 v176, 0x20c00, v96
	ds_read2st64_b32 v[96:97], v152 offset1:4
	ds_read2st64_b32 v[98:99], v152 offset0:8 offset1:12
	ds_read_b32 v116, v174
	ds_read_b32 v117, v175
	ds_read_b32 v118, v176
	global_load_dwordx4 v[168:171], v[92:93], off offset:256 nt
	v_or_b32_e32 v154, 16, v162
	v_mad_i64_i32 v[112:113], s[22:23], v154, s77, v[94:95]
	v_lshl_add_u64 v[92:93], v[112:113], 0, v[158:159]
	v_lshl_add_u64 v[234:235], v[92:93], 0, s[98:99]
	global_load_dwordx4 v[136:139], v[92:93], off nt
	global_load_dwordx4 v[132:135], v[92:93], off offset:256 nt
	s_waitcnt lgkmcnt(0)
	v_add_f32_e32 v92, v96, v97
	v_add_f32_e32 v92, v92, v98
	v_or_b32_e32 v160, 32, v162
	v_or_b32_e32 v163, 48, v162
	v_add_f32_e32 v92, v92, v99
	v_mad_i64_i32 v[114:115], s[22:23], v160, s77, v[94:95]
	v_mad_i64_i32 v[94:95], s[22:23], v163, s77, v[94:95]
	v_max_f32_e32 v93, v118, v118
	v_fmac_f32_e32 v92, v116, v117
	v_lshl_add_u64 v[112:113], v[114:115], 0, v[158:159]
	v_lshl_add_u64 v[94:95], v[94:95], 0, v[158:159]
	v_max_f32_e64 v92, |v92|, v93
	v_rcp_f32_e32 v156, v92
	v_lshl_add_u64 v[236:237], v[112:113], 0, s[98:99]
	global_load_dwordx4 v[116:119], v[112:113], off nt
	s_nop 0
	global_load_dwordx4 v[112:115], v[112:113], off offset:256 nt
	s_nop 0
	v_lshl_add_u64 v[238:239], v[94:95], 0, s[98:99]
	global_load_dwordx4 v[96:99], v[94:95], off nt
	s_nop 0
	global_load_dwordx4 v[92:95], v[94:95], off offset:256 nt
	global_load_dwordx4 v[200:203], v[232:233], off nt
	global_load_dwordx4 v[204:207], v[232:233], off offset:256 nt
	global_load_dwordx4 v[208:211], v[234:235], off nt
	global_load_dwordx4 v[212:215], v[234:235], off offset:256 nt
	global_load_dwordx4 v[216:219], v[236:237], off nt
	global_load_dwordx4 v[220:223], v[236:237], off offset:256 nt
	global_load_dwordx4 v[224:227], v[238:239], off nt
	global_load_dwordx4 v[228:231], v[238:239], off offset:256 nt
	s_lshl_b32 s3, s42, 8
	v_cmp_gt_u32_e32 vcc, 16, v155
	v_pk_mul_f32 v[150:151], v[150:151], v[156:157] op_sel_hi:[1,0]
	v_pk_mul_f32 v[148:149], v[148:149], v[156:157] op_sel_hi:[1,0]
	v_pk_mul_f32 v[178:179], v[30:31], v[156:157] op_sel_hi:[1,0]
	v_pk_mul_f32 v[180:181], v[28:29], v[156:157] op_sel_hi:[1,0]
	s_waitcnt vmcnt(8)
	v_lshlrev_b32_e32 v157, 16, v166
	v_lshlrev_b32_e32 v28, 16, v164
	v_and_b32_e32 v29, 0xffff0000, v164
	v_mul_f32_e32 v157, 0xbfb8aa3b, v157
	v_lshlrev_b32_e32 v30, 16, v165
	v_and_b32_e32 v31, 0xffff0000, v165
	v_and_b32_e32 v161, 0xffff0000, v166
	v_mul_f32_e32 v28, 0xbfb8aa3b, v28
	v_mul_f32_e32 v29, 0xbfb8aa3b, v29
	v_exp_f32_e32 v157, v157
	v_mul_f32_e32 v30, 0xbfb8aa3b, v30
	v_mul_f32_e32 v31, 0xbfb8aa3b, v31
	v_mul_f32_e32 v161, 0xbfb8aa3b, v161
	v_exp_f32_e32 v28, v28
	v_exp_f32_e32 v29, v29
	v_exp_f32_e32 v30, v30
	v_exp_f32_e32 v31, v31
	v_exp_f32_e32 v161, v161
	v_lshlrev_b32_e32 v164, 16, v167
	v_and_b32_e32 v165, 0xffff0000, v167
	v_mul_f32_e32 v164, 0xbfb8aa3b, v164
	v_add_f32_e32 v157, 1.0, v157
	v_exp_f32_e32 v166, v164
	v_add_f32_e32 v28, 1.0, v28
	v_add_f32_e32 v29, 1.0, v29
	v_rcp_f32_e32 v164, v157
	v_mul_f32_e32 v157, 0xbfb8aa3b, v165
	v_add_f32_e32 v30, 1.0, v30
	v_add_f32_e32 v31, 1.0, v31
	v_add_f32_e32 v161, 1.0, v161
	v_rcp_f32_e32 v28, v28
	v_rcp_f32_e32 v29, v29
	v_exp_f32_e32 v157, v157
	v_rcp_f32_e32 v30, v30
	v_rcp_f32_e32 v31, v31
	v_rcp_f32_e32 v165, v161
	v_add_f32_e32 v161, 1.0, v166
	v_add_f32_e32 v157, 1.0, v157
	v_pk_mul_f32 v[28:29], v[28:29], v[148:149]
	v_rcp_f32_e32 v186, v161
	v_rcp_f32_e32 v187, v157
	v_pk_mul_f32 v[30:31], v[30:31], v[150:151]
	v_pk_mul_f32 v[166:167], v[164:165], v[180:181]
	v_add_f32_e32 v148, v28, v29
	v_lshlrev_b32_e32 v164, 16, v170
	v_add_f32_e32 v148, v30, v148
	v_mul_f32_e32 v164, 0xbfb8aa3b, v164
	v_and_b32_e32 v165, 0xffff0000, v170
	v_add_f32_e32 v148, v31, v148
	v_exp_f32_e32 v164, v164
	v_mul_f32_e32 v165, 0xbfb8aa3b, v165
	v_add_f32_e32 v148, v166, v148
	v_exp_f32_e32 v165, v165
	v_pk_mul_f32 v[150:151], v[186:187], v[178:179]
	v_add_f32_e32 v148, v167, v148
	v_add_f32_e32 v148, v150, v148
	v_add_f32_e32 v148, v151, v148
	v_add_f32_e32 v164, 1.0, v164
	v_add_f32_e32 v161, 0, v148
	v_lshlrev_b32_e32 v148, 16, v168
	v_and_b32_e32 v149, 0xffff0000, v168
	v_rcp_f32_e32 v168, v164
	v_add_f32_e32 v164, 1.0, v165
	v_lshlrev_b32_e32 v165, 16, v171
	v_pk_mul_f32 v[146:147], v[146:147], v[156:157] op_sel_hi:[1,0]
	v_pk_mul_f32 v[144:145], v[144:145], v[156:157] op_sel_hi:[1,0]
	v_pk_mul_f32 v[142:143], v[142:143], v[156:157] op_sel_hi:[1,0]
	v_mul_f32_e32 v148, 0xbfb8aa3b, v148
	v_mul_f32_e32 v149, 0xbfb8aa3b, v149
	v_pk_mul_f32 v[140:141], v[140:141], v[156:157] op_sel_hi:[1,0]
	v_lshlrev_b32_e32 v156, 16, v169
	v_and_b32_e32 v157, 0xffff0000, v169
	v_mul_f32_e32 v165, 0xbfb8aa3b, v165
	v_and_b32_e32 v169, 0xffff0000, v171
	v_exp_f32_e32 v148, v148
	v_exp_f32_e32 v149, v149
	v_mul_f32_e32 v156, 0xbfb8aa3b, v156
	v_mul_f32_e32 v157, 0xbfb8aa3b, v157
	v_exp_f32_e32 v165, v165
	v_mul_f32_e32 v169, 0xbfb8aa3b, v169
	v_exp_f32_e32 v156, v156
	v_exp_f32_e32 v157, v157
	v_exp_f32_e32 v170, v169
	v_add_f32_e32 v148, 1.0, v148
	v_add_f32_e32 v149, 1.0, v149
	v_rcp_f32_e32 v169, v164
	v_add_f32_e32 v164, 1.0, v165
	v_rcp_f32_e32 v148, v148
	v_rcp_f32_e32 v149, v149
	v_add_f32_e32 v156, 1.0, v156
	v_add_f32_e32 v157, 1.0, v157
	v_rcp_f32_e32 v190, v164
	v_add_f32_e32 v164, 1.0, v170
	v_rcp_f32_e32 v156, v156
	v_rcp_f32_e32 v157, v157
	v_rcp_f32_e32 v191, v164
	v_pk_mul_f32 v[170:171], v[148:149], v[144:145]
	v_pk_mul_f32 v[148:149], v[168:169], v[140:141]
	v_pk_mul_f32 v[164:165], v[156:157], v[146:147]
	v_pk_mul_f32 v[140:141], v[190:191], v[142:143]
	v_add_f32_e32 v142, v170, v171
	v_add_f32_e32 v142, v164, v142
	v_add_f32_e32 v142, v165, v142
	v_add_f32_e32 v142, v148, v142
	v_add_f32_e32 v142, v149, v142
	v_add_f32_e32 v142, v140, v142
	v_add_f32_e32 v142, v141, v142
	v_pk_mul_f32 v[178:179], v[28:29], v[28:29]
	v_add_f32_e32 v161, v142, v161
	v_pk_mul_f32 v[142:143], v[170:171], v[170:171]
	v_pk_mul_f32 v[180:181], v[30:31], v[30:31]
	v_pk_mul_f32 v[144:145], v[164:165], v[164:165]
	v_add_f32_e32 v142, v142, v143
	v_add_f32_e32 v143, v178, v179
	v_add_f32_e32 v142, v144, v142
	v_add_f32_e32 v143, v180, v143
	v_pk_mul_f32 v[186:187], v[166:167], v[166:167]
	v_pk_mul_f32 v[146:147], v[148:149], v[148:149]
	v_add_f32_e32 v142, v145, v142
	v_add_f32_e32 v143, v181, v143
	v_add_f32_e32 v142, v146, v142
	v_add_f32_e32 v143, v186, v143
	v_pk_mul_f32 v[188:189], v[150:151], v[150:151]
	v_pk_mul_f32 v[156:157], v[140:141], v[140:141]
	v_add_f32_e32 v142, v147, v142
	v_add_f32_e32 v143, v187, v143
	v_add_f32_e32 v142, v156, v142
	v_add_f32_e32 v143, v188, v143
	v_add_f32_e32 v142, v157, v142
	v_add_f32_e32 v143, v189, v143
	v_add_f32_e32 v145, v143, v142
	ds_bpermute_b32 v144, v172, v161
	ds_bpermute_b32 v146, v172, v145
	s_waitcnt lgkmcnt(0)
	v_add_f32_e32 v142, v161, v144
	v_add_f32_e32 v144, v145, v146
	ds_bpermute_b32 v143, v173, v142
	ds_bpermute_b32 v145, v173, v144
	v_add_u32_e32 v146, s3, v162
	v_lshl_add_u32 v177, v146, 2, 0
	s_and_saveexec_b64 s[22:23], vcc
	s_cbranch_execz .LBB0_665
	s_waitcnt lgkmcnt(1)
	v_add_f32_e32 v142, v142, v143
	s_waitcnt lgkmcnt(0)
	v_add_f32_e32 v143, v144, v145
	ds_write2st64_b32 v177, v142, v143 offset1:16

.LBB0_671:
	s_or_b64 exec, exec, s[22:23]
	v_add_u32_e32 v82, 0x80, v162
	s_waitcnt lgkmcnt(1)
	v_mov_b64_e32 v[80:81], s[0:1]
	s_waitcnt lgkmcnt(0)
	v_mad_i64_i32 v[82:83], s[0:1], v82, s77, v[80:81]
	v_lshl_add_u64 v[82:83], v[82:83], 0, v[158:159]
	s_waitcnt vmcnt(0)
	v_mov_b64_e32 v[124:125], v[200:201]
	v_mov_b64_e32 v[126:127], v[202:203]
	v_mov_b64_e32 v[144:145], v[204:205]
	v_mov_b64_e32 v[146:147], v[206:207]
	v_add_u32_e32 v82, 0x90, v162
	v_add_u32_e32 v84, 0xa0, v162
	v_add_u32_e32 v86, 0xb0, v162
	v_mad_i64_i32 v[82:83], s[0:1], v82, s77, v[80:81]
	v_mad_i64_i32 v[84:85], s[0:1], v84, s77, v[80:81]
	v_mad_i64_i32 v[80:81], s[0:1], v86, s77, v[80:81]
	ds_read2st64_b32 v[86:87], v152 offset0:2 offset1:6
	ds_read2st64_b32 v[88:89], v152 offset0:10 offset1:14
	ds_read_b32 v90, v174 offset:512
	ds_read_b32 v91, v175 offset:512
	ds_read_b32 v92, v176 offset:512
	v_lshl_add_u64 v[82:83], v[82:83], 0, v[158:159]
	v_mov_b64_e32 v[100:101], v[208:209]
	v_mov_b64_e32 v[102:103], v[210:211]
	v_mov_b64_e32 v[96:97], v[212:213]
	v_mov_b64_e32 v[98:99], v[214:215]
	s_waitcnt lgkmcnt(0)
	v_add_f32_e32 v82, v86, v87
	v_add_f32_e32 v82, v82, v88
	v_add_f32_e32 v82, v82, v89
	v_max_f32_e32 v83, v92, v92
	v_fmac_f32_e32 v82, v90, v91
	v_lshl_add_u64 v[84:85], v[84:85], 0, v[158:159]
	v_lshl_add_u64 v[80:81], v[80:81], 0, v[158:159]
	v_max_f32_e64 v82, |v82|, v83
	v_rcp_f32_e32 v112, v82
	v_mov_b64_e32 v[92:93], v[216:217]
	v_mov_b64_e32 v[94:95], v[218:219]
	v_mov_b64_e32 v[88:89], v[220:221]
	v_mov_b64_e32 v[90:91], v[222:223]
	s_nop 0
	v_mov_b64_e32 v[84:85], v[224:225]
	v_mov_b64_e32 v[86:87], v[226:227]
	s_nop 0
	v_mov_b64_e32 v[80:81], v[228:229]
	v_mov_b64_e32 v[82:83], v[230:231]
	v_pk_mul_f32 v[162:163], v[24:25], v[112:113] op_sel_hi:[1,0]
	v_pk_mul_f32 v[128:129], v[26:27], v[112:113] op_sel_hi:[1,0]
	v_pk_mul_f32 v[78:79], v[78:79], v[112:113] op_sel_hi:[1,0]
	v_pk_mul_f32 v[76:77], v[76:77], v[112:113] op_sel_hi:[1,0]
	v_pk_mul_f32 v[74:75], v[74:75], v[112:113] op_sel_hi:[1,0]
	v_pk_mul_f32 v[72:73], v[72:73], v[112:113] op_sel_hi:[1,0]
	v_pk_mul_f32 v[70:71], v[70:71], v[112:113] op_sel_hi:[1,0]
	v_lshlrev_b32_e32 v24, 16, v124
	v_and_b32_e32 v25, 0xffff0000, v124
	v_lshlrev_b32_e32 v26, 16, v125
	v_and_b32_e32 v27, 0xffff0000, v125
	v_mul_f32_e32 v24, 0xbfb8aa3b, v24
	v_mul_f32_e32 v25, 0xbfb8aa3b, v25
	v_mul_f32_e32 v26, 0xbfb8aa3b, v26
	v_mul_f32_e32 v27, 0xbfb8aa3b, v27
	v_exp_f32_e32 v24, v24
	v_exp_f32_e32 v25, v25
	v_lshlrev_b32_e32 v113, 16, v126
	v_and_b32_e32 v124, 0xffff0000, v126
	v_exp_f32_e32 v26, v26
	v_exp_f32_e32 v27, v27
	v_lshlrev_b32_e32 v125, 16, v127
	v_mul_f32_e32 v113, 0xbfb8aa3b, v113
	v_mul_f32_e32 v124, 0xbfb8aa3b, v124
	v_and_b32_e32 v126, 0xffff0000, v127
	v_mul_f32_e32 v125, 0xbfb8aa3b, v125
	v_exp_f32_e32 v113, v113
	v_exp_f32_e32 v124, v124
	v_mul_f32_e32 v126, 0xbfb8aa3b, v126
	v_exp_f32_e32 v125, v125
	v_add_f32_e32 v24, 1.0, v24
	v_add_f32_e32 v25, 1.0, v25
	v_exp_f32_e32 v126, v126
	v_add_f32_e32 v26, 1.0, v26
	v_add_f32_e32 v27, 1.0, v27
	v_rcp_f32_e32 v24, v24
	v_rcp_f32_e32 v25, v25
	v_lshlrev_b32_e32 v127, 16, v144
	v_rcp_f32_e32 v26, v26
	v_rcp_f32_e32 v27, v27
	v_mul_f32_e32 v178, 0xbfb8aa3b, v127
	v_add_f32_e32 v113, 1.0, v113
	v_add_f32_e32 v127, 1.0, v124
	v_add_f32_e32 v132, 1.0, v125
	v_rcp_f32_e32 v124, v113
	v_rcp_f32_e32 v125, v127
	v_add_f32_e32 v133, 1.0, v126
	v_pk_mul_f32 v[24:25], v[24:25], v[76:77]
	v_rcp_f32_e32 v126, v132
	v_rcp_f32_e32 v127, v133
	v_pk_mul_f32 v[26:27], v[26:27], v[78:79]
	v_add_f32_e32 v113, v24, v25
	v_add_f32_e32 v113, v26, v113
	v_pk_mul_f32 v[158:159], v[124:125], v[72:73]
	v_add_f32_e32 v113, v27, v113
	v_add_f32_e32 v113, v158, v113
	v_pk_mul_f32 v[132:133], v[126:127], v[74:75]
	v_add_f32_e32 v113, v159, v113
	v_add_f32_e32 v113, v132, v113
	v_and_b32_e32 v124, 0xffff0000, v144
	v_add_f32_e32 v113, v133, v113
	v_mul_f32_e32 v124, 0xbfb8aa3b, v124
	v_add_f32_e32 v179, 0, v113
	v_exp_f32_e32 v113, v178
	v_exp_f32_e32 v124, v124
	v_and_b32_e32 v125, 0xffff0000, v145
	v_lshlrev_b32_e32 v126, 16, v146
	v_pk_mul_f32 v[68:69], v[68:69], v[112:113] op_sel_hi:[1,0]
	v_add_f32_e32 v112, 1.0, v113
	v_add_f32_e32 v113, 1.0, v124
	v_lshlrev_b32_e32 v124, 16, v145
	v_and_b32_e32 v127, 0xffff0000, v146
	v_mul_f32_e32 v124, 0xbfb8aa3b, v124
	v_mul_f32_e32 v125, 0xbfb8aa3b, v125
	v_mul_f32_e32 v126, 0xbfb8aa3b, v126
	v_mul_f32_e32 v127, 0xbfb8aa3b, v127
	v_exp_f32_e32 v124, v124
	v_exp_f32_e32 v125, v125
	v_exp_f32_e32 v126, v126
	v_exp_f32_e32 v127, v127
	v_lshlrev_b32_e32 v144, 16, v147
	v_and_b32_e32 v145, 0xffff0000, v147
	v_mul_f32_e32 v144, 0xbfb8aa3b, v144
	v_mul_f32_e32 v145, 0xbfb8aa3b, v145
	v_rcp_f32_e32 v112, v112
	v_rcp_f32_e32 v113, v113
	v_add_f32_e32 v124, 1.0, v124
	v_add_f32_e32 v125, 1.0, v125
	v_add_f32_e32 v126, 1.0, v126
	v_add_f32_e32 v127, 1.0, v127
	v_exp_f32_e32 v144, v144
	v_exp_f32_e32 v145, v145
	v_rcp_f32_e32 v124, v124
	v_rcp_f32_e32 v125, v125
	v_rcp_f32_e32 v126, v126
	v_rcp_f32_e32 v127, v127
	v_add_f32_e32 v144, 1.0, v144
	v_add_f32_e32 v145, 1.0, v145
	v_pk_mul_f32 v[162:163], v[112:113], v[162:163]
	v_rcp_f32_e32 v144, v144
	v_rcp_f32_e32 v145, v145
	v_pk_mul_f32 v[146:147], v[124:125], v[128:129]
	v_pk_mul_f32 v[128:129], v[126:127], v[68:69]
	v_add_f32_e32 v68, v162, v163
	v_add_f32_e32 v68, v146, v68
	v_add_f32_e32 v68, v147, v68
	v_add_f32_e32 v68, v128, v68
	v_pk_mul_f32 v[112:113], v[144:145], v[70:71]
	v_add_f32_e32 v68, v129, v68
	v_add_f32_e32 v68, v112, v68
	v_add_f32_e32 v68, v113, v68
	v_pk_mul_f32 v[72:73], v[24:25], v[24:25]
	v_add_f32_e32 v144, v68, v179
	v_pk_mul_f32 v[68:69], v[162:163], v[162:163]
	v_pk_mul_f32 v[74:75], v[26:27], v[26:27]
	v_pk_mul_f32 v[70:71], v[146:147], v[146:147]
	v_add_f32_e32 v68, v68, v69
	v_add_f32_e32 v69, v72, v73
	v_add_f32_e32 v68, v70, v68
	v_add_f32_e32 v69, v74, v69
	v_pk_mul_f32 v[76:77], v[158:159], v[158:159]
	v_pk_mul_f32 v[124:125], v[128:129], v[128:129]
	v_add_f32_e32 v68, v71, v68
	v_add_f32_e32 v69, v75, v69
	v_add_f32_e32 v68, v124, v68
	v_add_f32_e32 v69, v76, v69
	v_pk_mul_f32 v[78:79], v[132:133], v[132:133]
	v_pk_mul_f32 v[126:127], v[112:113], v[112:113]
	v_add_f32_e32 v68, v125, v68
	v_add_f32_e32 v69, v77, v69
	v_add_f32_e32 v68, v126, v68
	v_add_f32_e32 v69, v78, v69
	v_add_f32_e32 v68, v127, v68
	v_add_f32_e32 v69, v79, v69
	v_add_f32_e32 v71, v69, v68
	ds_bpermute_b32 v70, v172, v144
	ds_bpermute_b32 v72, v172, v71
	s_waitcnt lgkmcnt(0)
	v_add_f32_e32 v68, v144, v70
	v_add_f32_e32 v70, v71, v72
	ds_bpermute_b32 v69, v173, v68
	ds_bpermute_b32 v71, v173, v70
	s_and_saveexec_b64 s[0:1], vcc
	s_cbranch_execz .LBB0_673
	s_waitcnt lgkmcnt(1)
	v_add_f32_e32 v68, v68, v69
	s_waitcnt lgkmcnt(0)
	v_add_f32_e32 v69, v70, v71
	ds_write2st64_b32 v177, v68, v69 offset0:2 offset1:18
